# merged GEMM K-loops: all ds_reads issued first in each load part, LDS-DMA issue after (reads-first order), no setprio
# speedup vs baseline: 1.0050x; 1.0050x over previous
; #define PG8_STAGE(bufoff, gbase, voff) do { _Pragma("unroll") for (int _i = 0; _i < 2; ++_i) \
;         __builtin_amdgcn_global_load_lds((const unsigned*)((const char*)(gbase) + (voff)[_i]), (LAS unsigned*)(lds + (bufoff) + ldsw + _i * 8192), 16, 0, 0); } while (0)
; #define PG8_LDA(dst, b, h) do { _Pragma("unroll") for (int m = 0; m < 4; ++m) _Pragma("unroll") for (int k = 0; k < 2; ++k) dst[m][k] = *(const LAS bf16x8*)(lds + PG8_SA(b, h) + aoff + m * 2048 + k * 1024); } while (0)
; #define PG8_LDB(dst, b, h) do { _Pragma("unroll") for (int n = 0; n < 2; ++n) _Pragma("unroll") for (int k = 0; k < 2; ++k) dst[n][k] = *(const LAS bf16x8*)(lds + PG8_SB(b, h) + boff + n * 2048 + k * 1024); } while (0)
; #define PG8_MMA(ai, bj, At, Bt) do { __builtin_amdgcn_s_setprio(1); _Pragma("unroll") for (int m = 0; m < 4; ++m) _Pragma("unroll") for (int n = 0; n < 2; ++n) _Pragma("unroll") for (int k = 0; k < 2; ++k) \
;         acc[ai][bj][m][n] = __builtin_amdgcn_mfma_f32_16x16x32_bf16(Bt[n][k], At[m][k], acc[ai][bj][m][n], 0, 0, 0); __builtin_amdgcn_s_setprio(0); } while (0)
; #define PG8_WAIT_V(n) asm volatile("s_waitcnt vmcnt(" #n ")" ::: "memory")
; #define PG8_WAIT_L(n) asm volatile("s_waitcnt lgkmcnt(" #n ")" ::: "memory")
; #define PG8_BAR __builtin_amdgcn_s_barrier()
; #define PG8_SCHED __builtin_amdgcn_sched_barrier(0)
; template <class Epi>
; __device__ __forceinline__ void gemm_phase(LAS unsigned char* lds, const Gemm g, const StaticOrder& S, const Epi& E) {
;     ...
;             PG8_LDB(B0, 0, 0); PG8_SCHED; PG8_LDA(At, 0, 0); PG8_STAGE(PG8_SA(1, 1), a1 + hstepA, voffA);
;             PG8_WAIT_L(8); PG8_BAR; PG8_WAIT_L(0); PG8_MMA(0, 0, At, B0); PG8_BAR; PG8_SCHED;
;             PG8_LDB(B1, 0, 1); PG8_STAGE(PG8_SB(0, 0), b2, voffB);
;             PG8_BAR; PG8_WAIT_L(0); PG8_MMA(0, 1, At, B1); PG8_BAR;
;             PG8_LDA(At, 0, 1); PG8_STAGE(PG8_SA(0, 0), a2, voffA);
;             PG8_BAR; PG8_WAIT_L(0); PG8_MMA(1, 0, At, B0); PG8_BAR; PG8_SCHED;
;             PG8_STAGE(PG8_SB(0, 1), b2 + hstepB, voffB);
;             PG8_WAIT_V(6); PG8_BAR; PG8_MMA(1, 1, At, B1); PG8_BAR;
.LBB0_119:
	s_add_u32 s55, s62, 0xfffc0080
	s_addc_u32 s61, s63, -1
	s_cmp_eq_u32 s33, 12
	s_cselect_b32 s67, s57, s61
	s_cselect_b32 s66, s56, s55
	s_cselect_b32 s65, s59, s31
	s_cselect_b32 s64, s58, s9
	ds_read_b128 v[146:149], v154
	ds_read_b128 v[158:161], v154 offset:1024
	ds_read_b128 v[162:165], v154 offset:2048
	ds_read_b128 v[166:169], v154 offset:3072
	ds_read_b128 v[170:173], v155
	ds_read_b128 v[174:177], v155 offset:1024
	ds_read_b128 v[178:181], v155 offset:2048
	ds_read_b128 v[182:185], v155 offset:3072
	ds_read_b128 v[186:189], v155 offset:4096
	ds_read_b128 v[190:193], v155 offset:5120
	ds_read_b128 v[194:197], v155 offset:6144
	ds_read_b128 v[198:201], v155 offset:7168
	ds_read_b128 v[202:205], v156
	ds_read_b128 v[206:209], v156 offset:1024
	ds_read_b128 v[210:213], v156 offset:2048
	ds_read_b128 v[214:217], v156 offset:3072
	v_lshl_add_u64 v[242:243], s[62:63], 0, v[138:139]
	s_add_i32 m0, s68, 0xc000
	global_load_lds_dwordx4 v[242:243], off
	v_lshl_add_u64 v[242:243], s[62:63], 0, v[140:141]
	s_add_i32 m0, s68, 0xe000
	s_nop 0
	global_load_lds_dwordx4 v[242:243], off
	s_waitcnt vmcnt(8) lgkmcnt(0)
	s_barrier
	v_mfma_f32_16x16x32_bf16 v[124:127], v[146:149], v[170:173], v[124:127]
	v_mfma_f32_16x16x32_bf16 v[120:123], v[162:165], v[170:173], v[120:123]
	v_mfma_f32_16x16x32_bf16 v[108:111], v[146:149], v[178:181], v[108:111]
	v_mfma_f32_16x16x32_bf16 v[104:107], v[162:165], v[178:181], v[104:107]
	v_mfma_f32_16x16x32_bf16 v[92:95], v[146:149], v[186:189], v[92:95]
	v_mfma_f32_16x16x32_bf16 v[88:91], v[162:165], v[186:189], v[88:91]
	v_mfma_f32_16x16x32_bf16 v[76:79], v[146:149], v[194:197], v[76:79]
	v_mfma_f32_16x16x32_bf16 v[72:75], v[162:165], v[194:197], v[72:75]
	v_mfma_f32_16x16x32_bf16 v[124:127], v[158:161], v[174:177], v[124:127]
	v_mfma_f32_16x16x32_bf16 v[120:123], v[166:169], v[174:177], v[120:123]
	v_mfma_f32_16x16x32_bf16 v[108:111], v[158:161], v[182:185], v[108:111]
	v_mfma_f32_16x16x32_bf16 v[104:107], v[166:169], v[182:185], v[104:107]
	v_mfma_f32_16x16x32_bf16 v[92:95], v[158:161], v[190:193], v[92:95]
	v_mfma_f32_16x16x32_bf16 v[88:91], v[166:169], v[190:193], v[88:91]
	v_mfma_f32_16x16x32_bf16 v[76:79], v[158:161], v[198:201], v[76:79]
	v_mfma_f32_16x16x32_bf16 v[72:75], v[166:169], v[198:201], v[72:75]
	v_mfma_f32_16x16x32_bf16 v[116:119], v[202:205], v[170:173], v[116:119]
	v_mfma_f32_16x16x32_bf16 v[112:115], v[210:213], v[170:173], v[112:115]
	v_mfma_f32_16x16x32_bf16 v[100:103], v[202:205], v[178:181], v[100:103]
	v_mfma_f32_16x16x32_bf16 v[96:99], v[210:213], v[178:181], v[96:99]
	v_mfma_f32_16x16x32_bf16 v[84:87], v[202:205], v[186:189], v[84:87]
	v_mfma_f32_16x16x32_bf16 v[80:83], v[210:213], v[186:189], v[80:83]
	v_mfma_f32_16x16x32_bf16 v[68:71], v[202:205], v[194:197], v[68:71]
	v_mfma_f32_16x16x32_bf16 v[64:67], v[210:213], v[194:197], v[64:67]
	v_mfma_f32_16x16x32_bf16 v[116:119], v[206:209], v[174:177], v[116:119]
	v_mfma_f32_16x16x32_bf16 v[112:115], v[214:217], v[174:177], v[112:115]
	v_mfma_f32_16x16x32_bf16 v[100:103], v[206:209], v[182:185], v[100:103]
	v_mfma_f32_16x16x32_bf16 v[96:99], v[214:217], v[182:185], v[96:99]
	v_mfma_f32_16x16x32_bf16 v[84:87], v[206:209], v[190:193], v[84:87]
	v_mfma_f32_16x16x32_bf16 v[80:83], v[214:217], v[190:193], v[80:83]
	v_mfma_f32_16x16x32_bf16 v[68:71], v[206:209], v[198:201], v[68:71]
	v_mfma_f32_16x16x32_bf16 v[64:67], v[214:217], v[198:201], v[64:67]
	s_barrier
	ds_read_b128 v[170:173], v155 offset:16384
	ds_read_b128 v[174:177], v155 offset:17408
	ds_read_b128 v[178:181], v155 offset:18432
	ds_read_b128 v[182:185], v155 offset:19456
	ds_read_b128 v[186:189], v155 offset:20480
	ds_read_b128 v[190:193], v155 offset:21504
	ds_read_b128 v[194:197], v155 offset:22528
	ds_read_b128 v[198:201], v155 offset:23552
	s_add_i32 s55, s78, s35
	v_lshl_add_u64 v[218:219], s[64:65], 0, v[132:133]
	s_mov_b32 m0, s55
	global_load_lds_dwordx4 v[218:219], off
	v_lshl_add_u64 v[220:221], s[64:65], 0, v[136:137]
	s_add_i32 m0, s55, 0x2000
	s_nop 0
	global_load_lds_dwordx4 v[220:221], off
	s_mov_b32 m0, s68
	v_lshl_add_u64 v[222:223], s[66:67], 0, v[130:131]
	global_load_lds_dwordx4 v[222:223], off
	v_lshl_add_u64 v[224:225], s[66:67], 0, v[134:135]
	s_mov_b32 m0, s69
	s_nop 0
	global_load_lds_dwordx4 v[224:225], off
	s_add_u32 s82, s64, 0x40000
	s_addc_u32 s83, s65, 0
	s_add_i32 s55, s79, s35
	v_lshl_add_u64 v[240:241], s[82:83], 0, v[132:133]
	s_mov_b32 m0, s55
	s_nop 0
	global_load_lds_dwordx4 v[240:241], off
	v_lshl_add_u64 v[240:241], s[82:83], 0, v[136:137]
	s_add_i32 m0, s55, 0x2000
	s_nop 0
	global_load_lds_dwordx4 v[240:241], off
	s_waitcnt vmcnt(8) lgkmcnt(0)
	s_barrier
; #define PG8_STAGE(bufoff, gbase, voff) do { _Pragma("unroll") for (int _i = 0; _i < 2; ++_i) \
;         __builtin_amdgcn_global_load_lds((const unsigned*)((const char*)(gbase) + (voff)[_i]), (LAS unsigned*)(lds + (bufoff) + ldsw + _i * 8192), 16, 0, 0); } while (0)
; #define PG8_LDA(dst, b, h) do { _Pragma("unroll") for (int m = 0; m < 4; ++m) _Pragma("unroll") for (int k = 0; k < 2; ++k) dst[m][k] = *(const LAS bf16x8*)(lds + PG8_SA(b, h) + aoff + m * 2048 + k * 1024); } while (0)
; #define PG8_LDB(dst, b, h) do { _Pragma("unroll") for (int n = 0; n < 2; ++n) _Pragma("unroll") for (int k = 0; k < 2; ++k) dst[n][k] = *(const LAS bf16x8*)(lds + PG8_SB(b, h) + boff + n * 2048 + k * 1024); } while (0)
; #define PG8_MMA(ai, bj, At, Bt) do { __builtin_amdgcn_s_setprio(1); _Pragma("unroll") for (int m = 0; m < 4; ++m) _Pragma("unroll") for (int n = 0; n < 2; ++n) _Pragma("unroll") for (int k = 0; k < 2; ++k) \
;         acc[ai][bj][m][n] = __builtin_amdgcn_mfma_f32_16x16x32_bf16(Bt[n][k], At[m][k], acc[ai][bj][m][n], 0, 0, 0); __builtin_amdgcn_s_setprio(0); } while (0)
; #define PG8_WAIT_L(n) asm volatile("s_waitcnt lgkmcnt(" #n ")" ::: "memory")
; #define PG8_BAR __builtin_amdgcn_s_barrier()
; #define PG8_SCHED __builtin_amdgcn_sched_barrier(0)
; template <class Epi>
; __device__ __forceinline__ void gemm_phase(LAS unsigned char* lds, const Gemm g, const StaticOrder& S, const Epi& E) {
;     ...
;             PG8_LDB(B0, 1, 0); PG8_SCHED; PG8_LDA(At, 1, 0); PG8_STAGE(PG8_SA(0, 1), a2 + hstepA, voffA);
;             PG8_WAIT_L(8); PG8_BAR; PG8_WAIT_L(0); PG8_MMA(0, 0, At, B0); PG8_BAR; PG8_SCHED;
;             PG8_LDB(B1, 1, 1); PG8_STAGE(PG8_SB(1, 0), b3, voffB);
;             PG8_BAR; PG8_WAIT_L(0); PG8_MMA(0, 1, At, B1); PG8_BAR;
;             PG8_LDA(At, 1, 1); PG8_STAGE(PG8_SA(1, 0), a3, voffA);
;             PG8_BAR; PG8_WAIT_L(0); PG8_MMA(1, 0, At, B0); PG8_BAR; PG8_SCHED;
	v_mfma_f32_16x16x32_bf16 v[60:63], v[146:149], v[170:173], v[60:63]
	v_mfma_f32_16x16x32_bf16 v[56:59], v[162:165], v[170:173], v[56:59]
	v_mfma_f32_16x16x32_bf16 v[44:47], v[146:149], v[178:181], v[44:47]
	v_mfma_f32_16x16x32_bf16 v[40:43], v[162:165], v[178:181], v[40:43]
	v_mfma_f32_16x16x32_bf16 v[28:31], v[146:149], v[186:189], v[28:31]
	v_mfma_f32_16x16x32_bf16 v[24:27], v[162:165], v[186:189], v[24:27]
	v_mfma_f32_16x16x32_bf16 v[12:15], v[146:149], v[194:197], v[12:15]
	v_mfma_f32_16x16x32_bf16 v[8:11], v[162:165], v[194:197], v[8:11]
	v_mfma_f32_16x16x32_bf16 v[60:63], v[158:161], v[174:177], v[60:63]
	v_mfma_f32_16x16x32_bf16 v[56:59], v[166:169], v[174:177], v[56:59]
	v_mfma_f32_16x16x32_bf16 v[44:47], v[158:161], v[182:185], v[44:47]
	v_mfma_f32_16x16x32_bf16 v[40:43], v[166:169], v[182:185], v[40:43]
	v_mfma_f32_16x16x32_bf16 v[28:31], v[158:161], v[190:193], v[28:31]
	v_mfma_f32_16x16x32_bf16 v[24:27], v[166:169], v[190:193], v[24:27]
	v_mfma_f32_16x16x32_bf16 v[12:15], v[158:161], v[198:201], v[12:15]
	v_mfma_f32_16x16x32_bf16 v[8:11], v[166:169], v[198:201], v[8:11]
	v_mfma_f32_16x16x32_bf16 v[52:55], v[202:205], v[170:173], v[52:55]
	v_mfma_f32_16x16x32_bf16 v[48:51], v[210:213], v[170:173], v[48:51]
	v_mfma_f32_16x16x32_bf16 v[36:39], v[202:205], v[178:181], v[36:39]
	v_mfma_f32_16x16x32_bf16 v[32:35], v[210:213], v[178:181], v[32:35]
	v_mfma_f32_16x16x32_bf16 v[20:23], v[202:205], v[186:189], v[20:23]
	v_mfma_f32_16x16x32_bf16 v[16:19], v[210:213], v[186:189], v[16:19]
	v_mfma_f32_16x16x32_bf16 v[4:7], v[202:205], v[194:197], v[4:7]
	v_mfma_f32_16x16x32_bf16 v[0:3], v[210:213], v[194:197], v[0:3]
	v_mfma_f32_16x16x32_bf16 v[52:55], v[206:209], v[174:177], v[52:55]
	v_mfma_f32_16x16x32_bf16 v[48:51], v[214:217], v[174:177], v[48:51]
	v_mfma_f32_16x16x32_bf16 v[36:39], v[206:209], v[182:185], v[36:39]
	v_mfma_f32_16x16x32_bf16 v[32:35], v[214:217], v[182:185], v[32:35]
	v_mfma_f32_16x16x32_bf16 v[20:23], v[206:209], v[190:193], v[20:23]
	v_mfma_f32_16x16x32_bf16 v[16:19], v[214:217], v[190:193], v[16:19]
	v_mfma_f32_16x16x32_bf16 v[4:7], v[206:209], v[198:201], v[4:7]
	v_mfma_f32_16x16x32_bf16 v[0:3], v[214:217], v[198:201], v[0:3]
	s_barrier
	s_add_i32 s55, 0, 0x18000
	v_add_u32_e32 v157, s55, v152
	ds_read_b128 v[146:149], v157
	ds_read_b128 v[158:161], v157 offset:1024
	ds_read_b128 v[162:165], v157 offset:2048
	ds_read_b128 v[166:169], v157 offset:3072
	ds_read_b128 v[170:173], v155 offset:32768
	ds_read_b128 v[174:177], v155 offset:33792
	ds_read_b128 v[178:181], v155 offset:34816
	ds_read_b128 v[182:185], v155 offset:35840
	ds_read_b128 v[186:189], v155 offset:36864
	ds_read_b128 v[190:193], v155 offset:37888
	ds_read_b128 v[194:197], v155 offset:38912
	ds_read_b128 v[198:201], v155 offset:39936
	s_add_i32 s98, 0, 0x1c000
	v_add_u32_e32 v157, s98, v152
	ds_read_b128 v[202:205], v157
	ds_read_b128 v[206:209], v157 offset:1024
	ds_read_b128 v[210:213], v157 offset:2048
	ds_read_b128 v[214:217], v157 offset:3072
	s_add_u32 s66, s66, 0x40000
	s_addc_u32 s67, s67, 0
	s_mov_b32 m0, s70
	v_lshl_add_u64 v[244:245], s[66:67], 0, v[130:131]
	global_load_lds_dwordx4 v[244:245], off
	v_lshl_add_u64 v[244:245], s[66:67], 0, v[134:135]
	s_mov_b32 m0, s71
	s_nop 0
	global_load_lds_dwordx4 v[244:245], off
	s_waitcnt vmcnt(8) lgkmcnt(0)
	s_barrier
	v_mfma_f32_16x16x32_bf16 v[124:127], v[146:149], v[170:173], v[124:127]
	v_mfma_f32_16x16x32_bf16 v[120:123], v[162:165], v[170:173], v[120:123]
	v_mfma_f32_16x16x32_bf16 v[108:111], v[146:149], v[178:181], v[108:111]
	v_mfma_f32_16x16x32_bf16 v[104:107], v[162:165], v[178:181], v[104:107]
	v_mfma_f32_16x16x32_bf16 v[92:95], v[146:149], v[186:189], v[92:95]
	v_mfma_f32_16x16x32_bf16 v[88:91], v[162:165], v[186:189], v[88:91]
	v_mfma_f32_16x16x32_bf16 v[76:79], v[146:149], v[194:197], v[76:79]
	v_mfma_f32_16x16x32_bf16 v[72:75], v[162:165], v[194:197], v[72:75]
	v_mfma_f32_16x16x32_bf16 v[124:127], v[158:161], v[174:177], v[124:127]
	v_mfma_f32_16x16x32_bf16 v[120:123], v[166:169], v[174:177], v[120:123]
	v_mfma_f32_16x16x32_bf16 v[108:111], v[158:161], v[182:185], v[108:111]
	v_mfma_f32_16x16x32_bf16 v[104:107], v[166:169], v[182:185], v[104:107]
	v_mfma_f32_16x16x32_bf16 v[92:95], v[158:161], v[190:193], v[92:95]
	v_mfma_f32_16x16x32_bf16 v[88:91], v[166:169], v[190:193], v[88:91]
	v_mfma_f32_16x16x32_bf16 v[76:79], v[158:161], v[198:201], v[76:79]
	v_mfma_f32_16x16x32_bf16 v[72:75], v[166:169], v[198:201], v[72:75]
	v_mfma_f32_16x16x32_bf16 v[116:119], v[202:205], v[170:173], v[116:119]
	v_mfma_f32_16x16x32_bf16 v[112:115], v[210:213], v[170:173], v[112:115]
	v_mfma_f32_16x16x32_bf16 v[100:103], v[202:205], v[178:181], v[100:103]
	v_mfma_f32_16x16x32_bf16 v[96:99], v[210:213], v[178:181], v[96:99]
	v_mfma_f32_16x16x32_bf16 v[84:87], v[202:205], v[186:189], v[84:87]
	v_mfma_f32_16x16x32_bf16 v[80:83], v[210:213], v[186:189], v[80:83]
	v_mfma_f32_16x16x32_bf16 v[68:71], v[202:205], v[194:197], v[68:71]
	v_mfma_f32_16x16x32_bf16 v[64:67], v[210:213], v[194:197], v[64:67]
	v_mfma_f32_16x16x32_bf16 v[116:119], v[206:209], v[174:177], v[116:119]
	v_mfma_f32_16x16x32_bf16 v[112:115], v[214:217], v[174:177], v[112:115]
	v_mfma_f32_16x16x32_bf16 v[100:103], v[206:209], v[182:185], v[100:103]
	v_mfma_f32_16x16x32_bf16 v[96:99], v[214:217], v[182:185], v[96:99]
	v_mfma_f32_16x16x32_bf16 v[84:87], v[206:209], v[190:193], v[84:87]
	v_mfma_f32_16x16x32_bf16 v[80:83], v[214:217], v[190:193], v[80:83]
	v_mfma_f32_16x16x32_bf16 v[68:71], v[206:209], v[198:201], v[68:71]
	v_mfma_f32_16x16x32_bf16 v[64:67], v[214:217], v[198:201], v[64:67]
	s_barrier
; __device__ __forceinline__ float gelu_t(float x) { return x * __builtin_amdgcn_rcpf(1.f + __expf(-1.5957691216057308f * (x + 0.044715f * x * x * x))); }
; #define PG8_STAGE(bufoff, gbase, voff) do { _Pragma("unroll") for (int _i = 0; _i < 2; ++_i) \
;         __builtin_amdgcn_global_load_lds((const unsigned*)((const char*)(gbase) + (voff)[_i]), (LAS unsigned*)(lds + (bufoff) + ldsw + _i * 8192), 16, 0, 0); } while (0)
; #define PG8_MMA(ai, bj, At, Bt) do { __builtin_amdgcn_s_setprio(1); _Pragma("unroll") for (int m = 0; m < 4; ++m) _Pragma("unroll") for (int n = 0; n < 2; ++n) _Pragma("unroll") for (int k = 0; k < 2; ++k) \
;         acc[ai][bj][m][n] = __builtin_amdgcn_mfma_f32_16x16x32_bf16(Bt[n][k], At[m][k], acc[ai][bj][m][n], 0, 0, 0); __builtin_amdgcn_s_setprio(0); } while (0)
; #define PG8_WAIT_V(n) asm volatile("s_waitcnt vmcnt(" #n ")" ::: "memory")
; #define PG8_BAR __builtin_amdgcn_s_barrier()
;     __device__ __forceinline__ void operator()(const f32x4 (&acc)[2][2][4][2], const Unit& u, int wr, int wc, int fr, int fq) const {
;     ...
;         for (int ai = 0; ai < 2; ++ai)
; #pragma unroll
;             for (int m = 0; m < 4; ++m) { const int row = row0 + ai * HALF + m * 16; u16* rowp = O + (size_t)row * ldc + col0;
; #pragma unroll
;                 for (int bj = 0; bj < 2; ++bj) { f32x4 v0 = acc[ai][bj][m][0], v1 = acc[ai][bj][m][1];
;                     if (col0 + bj * HALF >= gelu_from) { v0 = (f32x4){gelu_t(v0.x), gelu_t(v0.y), gelu_t(v0.z), gelu_t(v0.w)}; v1 = (f32x4){gelu_t(v1.x), gelu_t(v1.y), gelu_t(v1.z), gelu_t(v1.w)}; }
; template <class Epi>
; __device__ __forceinline__ void gemm_phase(LAS unsigned char* lds, const Gemm g, const StaticOrder& S, const Epi& E) {
;     ...
;             PG8_STAGE(PG8_SB(1, 1), b3 + hstepB, voffB);
;             PG8_WAIT_V(6); PG8_BAR; PG8_MMA(1, 1, At, B1); PG8_BAR;
	ds_read_b128 v[170:173], v155 offset:49152
	ds_read_b128 v[174:177], v155 offset:50176
	ds_read_b128 v[178:181], v155 offset:51200
	ds_read_b128 v[182:185], v155 offset:52224
	ds_read_b128 v[186:189], v155 offset:53248
	ds_read_b128 v[190:193], v155 offset:54272
	ds_read_b128 v[194:197], v155 offset:55296
	ds_read_b128 v[198:201], v155 offset:56320
	s_add_i32 s55, s55, s35
	v_lshl_add_u64 v[218:219], v[218:219], 0, s[28:29]
	s_mov_b32 m0, s55
	global_load_lds_dwordx4 v[218:219], off
	v_lshl_add_u64 v[218:219], v[220:221], 0, s[28:29]
	s_add_i32 m0, s55, 0x2000
	s_nop 0
	global_load_lds_dwordx4 v[218:219], off
	s_mov_b32 m0, s73
	v_lshl_add_u64 v[218:219], v[222:223], 0, s[28:29]
	global_load_lds_dwordx4 v[218:219], off
	v_lshl_add_u64 v[218:219], v[224:225], 0, s[28:29]
	s_mov_b32 m0, s74
	s_nop 0
	global_load_lds_dwordx4 v[218:219], off
	s_add_u32 s64, s64, 0x40080
	s_addc_u32 s65, s65, 0
	s_add_i32 s55, s98, s35
	v_lshl_add_u64 v[240:241], s[64:65], 0, v[132:133]
	s_mov_b32 m0, s55
	s_nop 0
	global_load_lds_dwordx4 v[240:241], off
	v_lshl_add_u64 v[240:241], s[64:65], 0, v[136:137]
	s_add_i32 m0, s55, 0x2000
	s_nop 0
	global_load_lds_dwordx4 v[240:241], off
	s_waitcnt vmcnt(8) lgkmcnt(0)
	s_barrier
	v_mfma_f32_16x16x32_bf16 v[60:63], v[146:149], v[170:173], v[60:63]
	v_mfma_f32_16x16x32_bf16 v[56:59], v[162:165], v[170:173], v[56:59]
	v_mfma_f32_16x16x32_bf16 v[44:47], v[146:149], v[178:181], v[44:47]
	v_mfma_f32_16x16x32_bf16 v[40:43], v[162:165], v[178:181], v[40:43]
	v_mfma_f32_16x16x32_bf16 v[28:31], v[146:149], v[186:189], v[28:31]
	v_mfma_f32_16x16x32_bf16 v[24:27], v[162:165], v[186:189], v[24:27]
	v_mfma_f32_16x16x32_bf16 v[12:15], v[146:149], v[194:197], v[12:15]
	v_mfma_f32_16x16x32_bf16 v[8:11], v[162:165], v[194:197], v[8:11]
	v_mfma_f32_16x16x32_bf16 v[60:63], v[158:161], v[174:177], v[60:63]
	v_mfma_f32_16x16x32_bf16 v[56:59], v[166:169], v[174:177], v[56:59]
	v_mfma_f32_16x16x32_bf16 v[44:47], v[158:161], v[182:185], v[44:47]
	v_mfma_f32_16x16x32_bf16 v[40:43], v[166:169], v[182:185], v[40:43]
	v_mfma_f32_16x16x32_bf16 v[28:31], v[158:161], v[190:193], v[28:31]
	v_mfma_f32_16x16x32_bf16 v[24:27], v[166:169], v[190:193], v[24:27]
	v_mfma_f32_16x16x32_bf16 v[12:15], v[158:161], v[198:201], v[12:15]
	v_mfma_f32_16x16x32_bf16 v[8:11], v[166:169], v[198:201], v[8:11]
	v_mfma_f32_16x16x32_bf16 v[52:55], v[202:205], v[170:173], v[52:55]
	v_mfma_f32_16x16x32_bf16 v[48:51], v[210:213], v[170:173], v[48:51]
	v_mfma_f32_16x16x32_bf16 v[36:39], v[202:205], v[178:181], v[36:39]
	v_mfma_f32_16x16x32_bf16 v[32:35], v[210:213], v[178:181], v[32:35]
	v_mfma_f32_16x16x32_bf16 v[20:23], v[202:205], v[186:189], v[20:23]
	v_mfma_f32_16x16x32_bf16 v[16:19], v[210:213], v[186:189], v[16:19]
	v_mfma_f32_16x16x32_bf16 v[4:7], v[202:205], v[194:197], v[4:7]
	v_mfma_f32_16x16x32_bf16 v[0:3], v[210:213], v[194:197], v[0:3]
	v_mfma_f32_16x16x32_bf16 v[52:55], v[206:209], v[174:177], v[52:55]
	v_mfma_f32_16x16x32_bf16 v[48:51], v[214:217], v[174:177], v[48:51]
	v_mfma_f32_16x16x32_bf16 v[36:39], v[206:209], v[182:185], v[36:39]
	v_mfma_f32_16x16x32_bf16 v[32:35], v[214:217], v[182:185], v[32:35]
	v_mfma_f32_16x16x32_bf16 v[20:23], v[206:209], v[190:193], v[20:23]
	v_mfma_f32_16x16x32_bf16 v[16:19], v[214:217], v[190:193], v[16:19]
	v_mfma_f32_16x16x32_bf16 v[4:7], v[206:209], v[198:201], v[4:7]
	v_mfma_f32_16x16x32_bf16 v[0:3], v[214:217], v[198:201], v[0:3]
	s_add_i32 s33, s33, 2
	s_add_u32 s62, s62, 0x100
	s_addc_u32 s63, s63, 0
	s_add_u32 s9, s9, 0x100
	s_addc_u32 s31, s31, 0
	s_cmp_gt_u32 s33, 13
	s_barrier
	s_cbranch_scc0 .LBB0_119
	v_lshl_or_b32 v146, s60, 8, v153
	v_cmp_lt_i32_e32 vcc, s80, v146
	s_and_saveexec_b64 s[60:61], vcc
	s_cbranch_execz .LBB0_122
	v_mul_f32_e32 v148, 0x3d372713, v125
	v_mul_f32_e32 v148, v125, v148
	v_fma_f32 v148, v125, v148, v125
	v_mul_f32_e32 v147, 0x3d372713, v124
	v_mul_f32_e32 v148, 0xbfcc422a, v148
	v_mul_f32_e32 v147, v124, v147
	v_mul_f32_e32 v148, 0x3fb8aa3b, v148
	v_fma_f32 v147, v124, v147, v124
	v_exp_f32_e32 v149, v148
	v_mul_f32_e32 v148, 0x3d372713, v126
	v_mul_f32_e32 v147, 0xbfcc422a, v147
	v_mul_f32_e32 v148, v126, v148
	v_mul_f32_e32 v147, 0x3fb8aa3b, v147
	v_fma_f32 v148, v126, v148, v126
	v_exp_f32_e32 v147, v147
	v_mul_f32_e32 v148, 0xbfcc422a, v148
	v_mul_f32_e32 v148, 0x3fb8aa3b, v148
	v_exp_f32_e32 v157, v148
	v_add_f32_e32 v147, 1.0, v147
	v_rcp_f32_e32 v148, v147
	v_add_f32_e32 v147, 1.0, v149
	v_rcp_f32_e32 v149, v147
	v_add_f32_e32 v147, 1.0, v157
	v_mul_f32_e32 v157, 0x3d372713, v127
	v_mul_f32_e32 v157, v127, v157
	v_mul_f32_e32 v158, 0x3d372713, v120
	v_fma_f32 v157, v127, v157, v127
	v_mul_f32_e32 v158, v120, v158
	v_mul_f32_e32 v157, 0xbfcc422a, v157
	v_fma_f32 v158, v120, v158, v120
	v_mul_f32_e32 v157, 0x3fb8aa3b, v157
	v_mul_f32_e32 v158, 0xbfcc422a, v158
	v_exp_f32_e32 v157, v157
	v_mul_f32_e32 v158, 0x3fb8aa3b, v158
	v_exp_f32_e32 v160, v158
	v_rcp_f32_e32 v158, v147
	v_add_f32_e32 v147, 1.0, v157
	v_rcp_f32_e32 v159, v147
	v_add_f32_e32 v147, 1.0, v160
	v_mul_f32_e32 v157, 0x3d372713, v122
	v_rcp_f32_e32 v160, v147
	v_mul_f32_e32 v147, 0x3d372713, v121
	v_mul_f32_e32 v157, v122, v157
	v_mul_f32_e32 v161, 0x3d372713, v123
	v_mul_f32_e32 v147, v121, v147
	v_fma_f32 v157, v122, v157, v122
	v_mul_f32_e32 v161, v123, v161
	v_fma_f32 v147, v121, v147, v121
	v_mul_f32_e32 v157, 0xbfcc422a, v157
	v_fma_f32 v161, v123, v161, v123
	v_mul_f32_e32 v147, 0xbfcc422a, v147
	v_mul_f32_e32 v157, 0x3fb8aa3b, v157
	v_mul_f32_e32 v161, 0xbfcc422a, v161
	v_mul_f32_e32 v147, 0x3fb8aa3b, v147
	v_exp_f32_e32 v157, v157
	v_mul_f32_e32 v161, 0x3fb8aa3b, v161
	v_exp_f32_e32 v147, v147
	v_exp_f32_e32 v161, v161
	v_add_f32_e32 v157, 1.0, v157
	v_rcp_f32_e32 v162, v157
	v_add_f32_e32 v147, 1.0, v147
	v_add_f32_e32 v157, 1.0, v161
	v_rcp_f32_e32 v163, v157
	v_rcp_f32_e32 v161, v147
	v_pk_mul_f32 v[126:127], v[126:127], v[158:159]
	v_pk_mul_f32 v[124:125], v[124:125], v[148:149]
	v_pk_mul_f32 v[122:123], v[122:123], v[162:163]
	v_pk_mul_f32 v[120:121], v[120:121], v[160:161]

; #define PG8_STAGE(bufoff, gbase, voff) do { _Pragma("unroll") for (int _i = 0; _i < 2; ++_i) \
;         __builtin_amdgcn_global_load_lds((const unsigned*)((const char*)(gbase) + (voff)[_i]), (LAS unsigned*)(lds + (bufoff) + ldsw + _i * 8192), 16, 0, 0); } while (0)
; #define PG8_LDA(dst, b, h) do { _Pragma("unroll") for (int m = 0; m < 4; ++m) _Pragma("unroll") for (int k = 0; k < 2; ++k) dst[m][k] = *(const LAS bf16x8*)(lds + PG8_SA(b, h) + aoff + m * 2048 + k * 1024); } while (0)
; #define PG8_LDB(dst, b, h) do { _Pragma("unroll") for (int n = 0; n < 2; ++n) _Pragma("unroll") for (int k = 0; k < 2; ++k) dst[n][k] = *(const LAS bf16x8*)(lds + PG8_SB(b, h) + boff + n * 2048 + k * 1024); } while (0)
; #define PG8_MMA(ai, bj, At, Bt) do { __builtin_amdgcn_s_setprio(1); _Pragma("unroll") for (int m = 0; m < 4; ++m) _Pragma("unroll") for (int n = 0; n < 2; ++n) _Pragma("unroll") for (int k = 0; k < 2; ++k) \
;         acc[ai][bj][m][n] = __builtin_amdgcn_mfma_f32_16x16x32_bf16(Bt[n][k], At[m][k], acc[ai][bj][m][n], 0, 0, 0); __builtin_amdgcn_s_setprio(0); } while (0)
; #define PG8_WAIT_V(n) asm volatile("s_waitcnt vmcnt(" #n ")" ::: "memory")
; #define PG8_WAIT_L(n) asm volatile("s_waitcnt lgkmcnt(" #n ")" ::: "memory")
; template <class Epi>
; __device__ __forceinline__ void gemm_phase(LAS unsigned char* lds, const Gemm g, const StaticOrder& S, const Epi& E) {
;     ...
;         for (int t = 0; t < nt; t += 2) {
;             const bool last = (t == nt - 2);
;             const char* a1 = cA + (size_t)(t + 1) * kstep;
;             const char* a2 = last ? nA : cA + (size_t)(t + 2) * kstep; const char* b2 = last ? nB : cB + (size_t)(t + 2) * kstep;
;             const char* a3 = a2 + kstep; const char* b3 = b2 + kstep;
;             PG8_LDB(B0, 0, 0); PG8_SCHED; PG8_LDA(At, 0, 0); PG8_STAGE(PG8_SA(1, 1), a1 + hstepA, voffA);
;             PG8_WAIT_L(8); PG8_BAR; PG8_WAIT_L(0); PG8_MMA(0, 0, At, B0); PG8_BAR; PG8_SCHED;
;             PG8_LDB(B1, 0, 1); PG8_STAGE(PG8_SB(0, 0), b2, voffB);
;             PG8_BAR; PG8_WAIT_L(0); PG8_MMA(0, 1, At, B1); PG8_BAR;
;             PG8_LDA(At, 0, 1); PG8_STAGE(PG8_SA(0, 0), a2, voffA);
;             PG8_BAR; PG8_WAIT_L(0); PG8_MMA(1, 0, At, B0); PG8_BAR; PG8_SCHED;
;             PG8_STAGE(PG8_SB(0, 1), b2 + hstepB, voffB);
;             PG8_WAIT_V(6); PG8_BAR; PG8_MMA(1, 1, At, B1); PG8_BAR;
.LBB0_456:
	s_add_i32 s85, s59, 2
	s_add_u32 s66, s64, 0xfffc0080
	s_addc_u32 s67, s65, -1
	s_cmp_eq_u32 s21, s59
	s_cselect_b32 s69, s63, s67
	s_cselect_b32 s68, s62, s66
	s_cselect_b32 s67, s1, s57
	s_cselect_b32 s66, s0, s31
	ds_read_b128 v[144:147], v158
	ds_read_b128 v[148:151], v158 offset:1024
	ds_read_b128 v[162:165], v158 offset:2048
	ds_read_b128 v[166:169], v158 offset:3072
	ds_read_b128 v[170:173], v159
	ds_read_b128 v[174:177], v159 offset:1024
	ds_read_b128 v[178:181], v159 offset:2048
	ds_read_b128 v[182:185], v159 offset:3072
	ds_read_b128 v[186:189], v159 offset:4096
	ds_read_b128 v[190:193], v159 offset:5120
	ds_read_b128 v[194:197], v159 offset:6144
	ds_read_b128 v[198:201], v159 offset:7168
	ds_read_b128 v[202:205], v160
	ds_read_b128 v[206:209], v160 offset:1024
	ds_read_b128 v[210:213], v160 offset:2048
	ds_read_b128 v[214:217], v160 offset:3072
	v_lshl_add_u64 v[152:153], s[64:65], 0, v[138:139]
	s_add_i32 m0, s35, 0xc000
	global_load_lds_dwordx4 v[152:153], off
	v_lshl_add_u64 v[152:153], s[64:65], 0, v[140:141]
	s_add_i32 m0, s35, 0xe000
	s_nop 0
	global_load_lds_dwordx4 v[152:153], off
	s_waitcnt vmcnt(8) lgkmcnt(0)
	s_barrier
	v_mfma_f32_16x16x32_bf16 v[124:127], v[144:147], v[170:173], v[124:127]
	v_mfma_f32_16x16x32_bf16 v[120:123], v[162:165], v[170:173], v[120:123]
	v_mfma_f32_16x16x32_bf16 v[116:119], v[144:147], v[178:181], v[116:119]
	v_mfma_f32_16x16x32_bf16 v[108:111], v[162:165], v[178:181], v[108:111]
	v_mfma_f32_16x16x32_bf16 v[100:103], v[144:147], v[186:189], v[100:103]
	v_mfma_f32_16x16x32_bf16 v[92:95], v[162:165], v[186:189], v[92:95]
	v_mfma_f32_16x16x32_bf16 v[84:87], v[144:147], v[194:197], v[84:87]
	v_mfma_f32_16x16x32_bf16 v[76:79], v[162:165], v[194:197], v[76:79]
	v_mfma_f32_16x16x32_bf16 v[124:127], v[148:151], v[174:177], v[124:127]
	v_mfma_f32_16x16x32_bf16 v[120:123], v[166:169], v[174:177], v[120:123]
	v_mfma_f32_16x16x32_bf16 v[116:119], v[148:151], v[182:185], v[116:119]
	v_mfma_f32_16x16x32_bf16 v[108:111], v[166:169], v[182:185], v[108:111]
	v_mfma_f32_16x16x32_bf16 v[100:103], v[148:151], v[190:193], v[100:103]
	v_mfma_f32_16x16x32_bf16 v[92:95], v[166:169], v[190:193], v[92:95]
	v_mfma_f32_16x16x32_bf16 v[84:87], v[148:151], v[198:201], v[84:87]
	v_mfma_f32_16x16x32_bf16 v[76:79], v[166:169], v[198:201], v[76:79]
	v_mfma_f32_16x16x32_bf16 v[112:115], v[202:205], v[170:173], v[112:115]
	v_mfma_f32_16x16x32_bf16 v[104:107], v[210:213], v[170:173], v[104:107]
	v_mfma_f32_16x16x32_bf16 v[96:99], v[202:205], v[178:181], v[96:99]
	v_mfma_f32_16x16x32_bf16 v[88:91], v[210:213], v[178:181], v[88:91]
	v_mfma_f32_16x16x32_bf16 v[80:83], v[202:205], v[186:189], v[80:83]
	v_mfma_f32_16x16x32_bf16 v[72:75], v[210:213], v[186:189], v[72:75]
	v_mfma_f32_16x16x32_bf16 v[68:71], v[202:205], v[194:197], v[68:71]
	v_mfma_f32_16x16x32_bf16 v[64:67], v[210:213], v[194:197], v[64:67]
	v_mfma_f32_16x16x32_bf16 v[112:115], v[206:209], v[174:177], v[112:115]
	v_mfma_f32_16x16x32_bf16 v[104:107], v[214:217], v[174:177], v[104:107]
	v_mfma_f32_16x16x32_bf16 v[96:99], v[206:209], v[182:185], v[96:99]
	v_mfma_f32_16x16x32_bf16 v[88:91], v[214:217], v[182:185], v[88:91]
	v_mfma_f32_16x16x32_bf16 v[80:83], v[206:209], v[190:193], v[80:83]
	v_mfma_f32_16x16x32_bf16 v[72:75], v[214:217], v[190:193], v[72:75]
	v_mfma_f32_16x16x32_bf16 v[68:71], v[206:209], v[198:201], v[68:71]
	v_mfma_f32_16x16x32_bf16 v[64:67], v[214:217], v[198:201], v[64:67]
	s_barrier
	ds_read_b128 v[170:173], v159 offset:16384
	ds_read_b128 v[174:177], v159 offset:17408
	ds_read_b128 v[178:181], v159 offset:18432
	ds_read_b128 v[182:185], v159 offset:19456
	ds_read_b128 v[186:189], v159 offset:20480
	ds_read_b128 v[190:193], v159 offset:21504
	ds_read_b128 v[194:197], v159 offset:22528
	ds_read_b128 v[198:201], v159 offset:23552
	s_add_i32 s59, s78, s33
	v_lshl_add_u64 v[152:153], s[66:67], 0, v[132:133]
	s_mov_b32 m0, s59
	global_load_lds_dwordx4 v[152:153], off
	v_lshl_add_u64 v[218:219], s[66:67], 0, v[136:137]
	s_add_i32 m0, s59, 0x2000
	s_nop 0
	global_load_lds_dwordx4 v[218:219], off
	s_mov_b32 m0, s35
	v_lshl_add_u64 v[220:221], s[68:69], 0, v[130:131]
	global_load_lds_dwordx4 v[220:221], off
	v_lshl_add_u64 v[222:223], s[68:69], 0, v[134:135]
	s_mov_b32 m0, s70
	s_nop 0
	global_load_lds_dwordx4 v[222:223], off
	s_add_u32 s86, s66, 0x40000
	s_addc_u32 s87, s67, 0
	s_add_i32 s59, s79, s33
	v_lshl_add_u64 v[240:241], s[86:87], 0, v[132:133]
	s_mov_b32 m0, s59
	s_nop 0
	global_load_lds_dwordx4 v[240:241], off
	v_lshl_add_u64 v[240:241], s[86:87], 0, v[136:137]
	s_add_i32 m0, s59, 0x2000
	s_nop 0
	global_load_lds_dwordx4 v[240:241], off
	s_waitcnt vmcnt(8) lgkmcnt(0)
	s_barrier
; #define PG8_STAGE(bufoff, gbase, voff) do { _Pragma("unroll") for (int _i = 0; _i < 2; ++_i) \
;         __builtin_amdgcn_global_load_lds((const unsigned*)((const char*)(gbase) + (voff)[_i]), (LAS unsigned*)(lds + (bufoff) + ldsw + _i * 8192), 16, 0, 0); } while (0)
; #define PG8_LDA(dst, b, h) do { _Pragma("unroll") for (int m = 0; m < 4; ++m) _Pragma("unroll") for (int k = 0; k < 2; ++k) dst[m][k] = *(const LAS bf16x8*)(lds + PG8_SA(b, h) + aoff + m * 2048 + k * 1024); } while (0)
; #define PG8_LDB(dst, b, h) do { _Pragma("unroll") for (int n = 0; n < 2; ++n) _Pragma("unroll") for (int k = 0; k < 2; ++k) dst[n][k] = *(const LAS bf16x8*)(lds + PG8_SB(b, h) + boff + n * 2048 + k * 1024); } while (0)
; #define PG8_MMA(ai, bj, At, Bt) do { __builtin_amdgcn_s_setprio(1); _Pragma("unroll") for (int m = 0; m < 4; ++m) _Pragma("unroll") for (int n = 0; n < 2; ++n) _Pragma("unroll") for (int k = 0; k < 2; ++k) \
;         acc[ai][bj][m][n] = __builtin_amdgcn_mfma_f32_16x16x32_bf16(Bt[n][k], At[m][k], acc[ai][bj][m][n], 0, 0, 0); __builtin_amdgcn_s_setprio(0); } while (0)
; #define PG8_WAIT_V(n) asm volatile("s_waitcnt vmcnt(" #n ")" ::: "memory")
; #define PG8_WAIT_L(n) asm volatile("s_waitcnt lgkmcnt(" #n ")" ::: "memory")
; #define PG8_BAR __builtin_amdgcn_s_barrier()
; #define PG8_SCHED __builtin_amdgcn_sched_barrier(0)
; template <class Epi>
; __device__ __forceinline__ void gemm_phase(LAS unsigned char* lds, const Gemm g, const StaticOrder& S, const Epi& E) {
;     ...
;             PG8_BAR; PG8_WAIT_L(0); PG8_MMA(1, 0, At, B0); PG8_BAR; PG8_SCHED;
;             PG8_STAGE(PG8_SB(0, 1), b2 + hstepB, voffB);
;             PG8_WAIT_V(6); PG8_BAR; PG8_MMA(1, 1, At, B1); PG8_BAR;
;             PG8_LDB(B0, 1, 0); PG8_SCHED; PG8_LDA(At, 1, 0); PG8_STAGE(PG8_SA(0, 1), a2 + hstepA, voffA);
;             PG8_WAIT_L(8); PG8_BAR; PG8_WAIT_L(0); PG8_MMA(0, 0, At, B0); PG8_BAR; PG8_SCHED;
;             PG8_LDB(B1, 1, 1); PG8_STAGE(PG8_SB(1, 0), b3, voffB);
;             PG8_BAR; PG8_WAIT_L(0); PG8_MMA(0, 1, At, B1); PG8_BAR;
	v_mfma_f32_16x16x32_bf16 v[60:63], v[144:147], v[170:173], v[60:63]
	v_mfma_f32_16x16x32_bf16 v[56:59], v[162:165], v[170:173], v[56:59]
	v_mfma_f32_16x16x32_bf16 v[52:55], v[144:147], v[178:181], v[52:55]
	v_mfma_f32_16x16x32_bf16 v[44:47], v[162:165], v[178:181], v[44:47]
	v_mfma_f32_16x16x32_bf16 v[36:39], v[144:147], v[186:189], v[36:39]
	v_mfma_f32_16x16x32_bf16 v[28:31], v[162:165], v[186:189], v[28:31]
	v_mfma_f32_16x16x32_bf16 v[20:23], v[144:147], v[194:197], v[20:23]
	v_mfma_f32_16x16x32_bf16 v[12:15], v[162:165], v[194:197], v[12:15]
	v_mfma_f32_16x16x32_bf16 v[60:63], v[148:151], v[174:177], v[60:63]
	v_mfma_f32_16x16x32_bf16 v[56:59], v[166:169], v[174:177], v[56:59]
	v_mfma_f32_16x16x32_bf16 v[52:55], v[148:151], v[182:185], v[52:55]
	v_mfma_f32_16x16x32_bf16 v[44:47], v[166:169], v[182:185], v[44:47]
	v_mfma_f32_16x16x32_bf16 v[36:39], v[148:151], v[190:193], v[36:39]
	v_mfma_f32_16x16x32_bf16 v[28:31], v[166:169], v[190:193], v[28:31]
	v_mfma_f32_16x16x32_bf16 v[20:23], v[148:151], v[198:201], v[20:23]
	v_mfma_f32_16x16x32_bf16 v[12:15], v[166:169], v[198:201], v[12:15]
	v_mfma_f32_16x16x32_bf16 v[48:51], v[202:205], v[170:173], v[48:51]
	v_mfma_f32_16x16x32_bf16 v[40:43], v[210:213], v[170:173], v[40:43]
	v_mfma_f32_16x16x32_bf16 v[32:35], v[202:205], v[178:181], v[32:35]
	v_mfma_f32_16x16x32_bf16 v[24:27], v[210:213], v[178:181], v[24:27]
	v_mfma_f32_16x16x32_bf16 v[16:19], v[202:205], v[186:189], v[16:19]
	v_mfma_f32_16x16x32_bf16 v[8:11], v[210:213], v[186:189], v[8:11]
	v_mfma_f32_16x16x32_bf16 v[4:7], v[202:205], v[194:197], v[4:7]
	v_mfma_f32_16x16x32_bf16 v[0:3], v[210:213], v[194:197], v[0:3]
	v_mfma_f32_16x16x32_bf16 v[48:51], v[206:209], v[174:177], v[48:51]
	v_mfma_f32_16x16x32_bf16 v[40:43], v[214:217], v[174:177], v[40:43]
	v_mfma_f32_16x16x32_bf16 v[32:35], v[206:209], v[182:185], v[32:35]
	v_mfma_f32_16x16x32_bf16 v[24:27], v[214:217], v[182:185], v[24:27]
	v_mfma_f32_16x16x32_bf16 v[16:19], v[206:209], v[190:193], v[16:19]
	v_mfma_f32_16x16x32_bf16 v[8:11], v[214:217], v[190:193], v[8:11]
	v_mfma_f32_16x16x32_bf16 v[4:7], v[206:209], v[198:201], v[4:7]
	v_mfma_f32_16x16x32_bf16 v[0:3], v[214:217], v[198:201], v[0:3]
	s_barrier
	s_add_i32 s59, 0, 0x18000
	v_add_u32_e32 v161, s59, v156
	ds_read_b128 v[144:147], v161
	ds_read_b128 v[148:151], v161 offset:1024
	ds_read_b128 v[162:165], v161 offset:2048
	ds_read_b128 v[166:169], v161 offset:3072
	ds_read_b128 v[170:173], v159 offset:32768
	ds_read_b128 v[174:177], v159 offset:33792
	ds_read_b128 v[178:181], v159 offset:34816
	ds_read_b128 v[182:185], v159 offset:35840
	ds_read_b128 v[186:189], v159 offset:36864
	ds_read_b128 v[190:193], v159 offset:37888
	ds_read_b128 v[194:197], v159 offset:38912
	ds_read_b128 v[198:201], v159 offset:39936
	s_add_i32 s98, 0, 0x1c000
	v_add_u32_e32 v161, s98, v156
	ds_read_b128 v[202:205], v161
	ds_read_b128 v[206:209], v161 offset:1024
	ds_read_b128 v[210:213], v161 offset:2048
	ds_read_b128 v[214:217], v161 offset:3072
	s_add_u32 s68, s68, 0x40000
	s_addc_u32 s69, s69, 0
	s_mov_b32 m0, s71
	v_lshl_add_u64 v[244:245], s[68:69], 0, v[130:131]
	global_load_lds_dwordx4 v[244:245], off
	v_lshl_add_u64 v[244:245], s[68:69], 0, v[134:135]
	s_mov_b32 m0, s72
	s_nop 0
	global_load_lds_dwordx4 v[244:245], off
	s_waitcnt vmcnt(8) lgkmcnt(0)
	s_barrier
	v_mfma_f32_16x16x32_bf16 v[124:127], v[144:147], v[170:173], v[124:127]
	v_mfma_f32_16x16x32_bf16 v[120:123], v[162:165], v[170:173], v[120:123]
	v_mfma_f32_16x16x32_bf16 v[116:119], v[144:147], v[178:181], v[116:119]
	v_mfma_f32_16x16x32_bf16 v[108:111], v[162:165], v[178:181], v[108:111]
	v_mfma_f32_16x16x32_bf16 v[100:103], v[144:147], v[186:189], v[100:103]
	v_mfma_f32_16x16x32_bf16 v[92:95], v[162:165], v[186:189], v[92:95]
	v_mfma_f32_16x16x32_bf16 v[84:87], v[144:147], v[194:197], v[84:87]
	v_mfma_f32_16x16x32_bf16 v[76:79], v[162:165], v[194:197], v[76:79]
	v_mfma_f32_16x16x32_bf16 v[124:127], v[148:151], v[174:177], v[124:127]
	v_mfma_f32_16x16x32_bf16 v[120:123], v[166:169], v[174:177], v[120:123]
	v_mfma_f32_16x16x32_bf16 v[116:119], v[148:151], v[182:185], v[116:119]
	v_mfma_f32_16x16x32_bf16 v[108:111], v[166:169], v[182:185], v[108:111]
	v_mfma_f32_16x16x32_bf16 v[100:103], v[148:151], v[190:193], v[100:103]
	v_mfma_f32_16x16x32_bf16 v[92:95], v[166:169], v[190:193], v[92:95]
	v_mfma_f32_16x16x32_bf16 v[84:87], v[148:151], v[198:201], v[84:87]
	v_mfma_f32_16x16x32_bf16 v[76:79], v[166:169], v[198:201], v[76:79]
	v_mfma_f32_16x16x32_bf16 v[112:115], v[202:205], v[170:173], v[112:115]
	v_mfma_f32_16x16x32_bf16 v[104:107], v[210:213], v[170:173], v[104:107]
	v_mfma_f32_16x16x32_bf16 v[96:99], v[202:205], v[178:181], v[96:99]
	v_mfma_f32_16x16x32_bf16 v[88:91], v[210:213], v[178:181], v[88:91]
	v_mfma_f32_16x16x32_bf16 v[80:83], v[202:205], v[186:189], v[80:83]
	v_mfma_f32_16x16x32_bf16 v[72:75], v[210:213], v[186:189], v[72:75]
	v_mfma_f32_16x16x32_bf16 v[68:71], v[202:205], v[194:197], v[68:71]
	v_mfma_f32_16x16x32_bf16 v[64:67], v[210:213], v[194:197], v[64:67]
	v_mfma_f32_16x16x32_bf16 v[112:115], v[206:209], v[174:177], v[112:115]
	v_mfma_f32_16x16x32_bf16 v[104:107], v[214:217], v[174:177], v[104:107]
	v_mfma_f32_16x16x32_bf16 v[96:99], v[206:209], v[182:185], v[96:99]
	v_mfma_f32_16x16x32_bf16 v[88:91], v[214:217], v[182:185], v[88:91]
	v_mfma_f32_16x16x32_bf16 v[80:83], v[206:209], v[190:193], v[80:83]
	v_mfma_f32_16x16x32_bf16 v[72:75], v[214:217], v[190:193], v[72:75]
	v_mfma_f32_16x16x32_bf16 v[68:71], v[206:209], v[198:201], v[68:71]
	v_mfma_f32_16x16x32_bf16 v[64:67], v[214:217], v[198:201], v[64:67]
	s_barrier
; #define PG8_STAGE(bufoff, gbase, voff) do { _Pragma("unroll") for (int _i = 0; _i < 2; ++_i) \
;         __builtin_amdgcn_global_load_lds((const unsigned*)((const char*)(gbase) + (voff)[_i]), (LAS unsigned*)(lds + (bufoff) + ldsw + _i * 8192), 16, 0, 0); } while (0)
; #define PG8_LDA(dst, b, h) do { _Pragma("unroll") for (int m = 0; m < 4; ++m) _Pragma("unroll") for (int k = 0; k < 2; ++k) dst[m][k] = *(const LAS bf16x8*)(lds + PG8_SA(b, h) + aoff + m * 2048 + k * 1024); } while (0)
; #define PG8_LDB(dst, b, h) do { _Pragma("unroll") for (int n = 0; n < 2; ++n) _Pragma("unroll") for (int k = 0; k < 2; ++k) dst[n][k] = *(const LAS bf16x8*)(lds + PG8_SB(b, h) + boff + n * 2048 + k * 1024); } while (0)
; #define PG8_MMA(ai, bj, At, Bt) do { __builtin_amdgcn_s_setprio(1); _Pragma("unroll") for (int m = 0; m < 4; ++m) _Pragma("unroll") for (int n = 0; n < 2; ++n) _Pragma("unroll") for (int k = 0; k < 2; ++k) \
;         acc[ai][bj][m][n] = __builtin_amdgcn_mfma_f32_16x16x32_bf16(Bt[n][k], At[m][k], acc[ai][bj][m][n], 0, 0, 0); __builtin_amdgcn_s_setprio(0); } while (0)
; #define PG8_WAIT_V(n) asm volatile("s_waitcnt vmcnt(" #n ")" ::: "memory")
; #define PG8_WAIT_L(n) asm volatile("s_waitcnt lgkmcnt(" #n ")" ::: "memory")
; #define PG8_BAR __builtin_amdgcn_s_barrier()
; #define PG8_SCHED __builtin_amdgcn_sched_barrier(0)
; template <class Epi>
; __device__ __forceinline__ void gemm_phase(LAS unsigned char* lds, const Gemm g, const StaticOrder& S, const Epi& E) {
;     ...
;             PG8_LDB(B1, 1, 1); PG8_STAGE(PG8_SB(1, 0), b3, voffB);
;             PG8_BAR; PG8_WAIT_L(0); PG8_MMA(0, 1, At, B1); PG8_BAR;
;             PG8_LDA(At, 1, 1); PG8_STAGE(PG8_SA(1, 0), a3, voffA);
;             PG8_BAR; PG8_WAIT_L(0); PG8_MMA(1, 0, At, B0); PG8_BAR; PG8_SCHED;
;             PG8_STAGE(PG8_SB(1, 1), b3 + hstepB, voffB);
;             PG8_WAIT_V(6); PG8_BAR; PG8_MMA(1, 1, At, B1); PG8_BAR;
;         }
	ds_read_b128 v[170:173], v159 offset:49152
	ds_read_b128 v[174:177], v159 offset:50176
	ds_read_b128 v[178:181], v159 offset:51200
	ds_read_b128 v[182:185], v159 offset:52224
	ds_read_b128 v[186:189], v159 offset:53248
	ds_read_b128 v[190:193], v159 offset:54272
	ds_read_b128 v[194:197], v159 offset:55296
	ds_read_b128 v[198:201], v159 offset:56320
	s_add_i32 s59, s59, s33
	v_lshl_add_u64 v[152:153], v[152:153], 0, s[12:13]
	s_mov_b32 m0, s59
	global_load_lds_dwordx4 v[152:153], off
	v_lshl_add_u64 v[152:153], v[218:219], 0, s[12:13]
	s_add_i32 m0, s59, 0x2000
	s_nop 0
	global_load_lds_dwordx4 v[152:153], off
	s_mov_b32 m0, s73
	v_lshl_add_u64 v[152:153], v[220:221], 0, s[12:13]
	global_load_lds_dwordx4 v[152:153], off
	v_lshl_add_u64 v[152:153], v[222:223], 0, s[12:13]
	s_mov_b32 m0, s74
	s_nop 0
	global_load_lds_dwordx4 v[152:153], off
	s_add_u32 s66, s66, 0x40080
	s_addc_u32 s67, s67, 0
	s_add_i32 s59, s98, s33
	v_lshl_add_u64 v[240:241], s[66:67], 0, v[132:133]
	s_mov_b32 m0, s59
	s_nop 0
	global_load_lds_dwordx4 v[240:241], off
	v_lshl_add_u64 v[240:241], s[66:67], 0, v[136:137]
	s_add_i32 m0, s59, 0x2000
	s_nop 0
	global_load_lds_dwordx4 v[240:241], off
	s_waitcnt vmcnt(8) lgkmcnt(0)
	s_barrier
	v_mfma_f32_16x16x32_bf16 v[60:63], v[144:147], v[170:173], v[60:63]
	v_mfma_f32_16x16x32_bf16 v[56:59], v[162:165], v[170:173], v[56:59]
	v_mfma_f32_16x16x32_bf16 v[52:55], v[144:147], v[178:181], v[52:55]
	v_mfma_f32_16x16x32_bf16 v[44:47], v[162:165], v[178:181], v[44:47]
	v_mfma_f32_16x16x32_bf16 v[36:39], v[144:147], v[186:189], v[36:39]
	v_mfma_f32_16x16x32_bf16 v[28:31], v[162:165], v[186:189], v[28:31]
	v_mfma_f32_16x16x32_bf16 v[20:23], v[144:147], v[194:197], v[20:23]
	v_mfma_f32_16x16x32_bf16 v[12:15], v[162:165], v[194:197], v[12:15]
	v_mfma_f32_16x16x32_bf16 v[60:63], v[148:151], v[174:177], v[60:63]
	v_mfma_f32_16x16x32_bf16 v[56:59], v[166:169], v[174:177], v[56:59]
	v_mfma_f32_16x16x32_bf16 v[52:55], v[148:151], v[182:185], v[52:55]
	v_mfma_f32_16x16x32_bf16 v[44:47], v[166:169], v[182:185], v[44:47]
	v_mfma_f32_16x16x32_bf16 v[36:39], v[148:151], v[190:193], v[36:39]
	v_mfma_f32_16x16x32_bf16 v[28:31], v[166:169], v[190:193], v[28:31]
	v_mfma_f32_16x16x32_bf16 v[20:23], v[148:151], v[198:201], v[20:23]
	v_mfma_f32_16x16x32_bf16 v[12:15], v[166:169], v[198:201], v[12:15]
	v_mfma_f32_16x16x32_bf16 v[48:51], v[202:205], v[170:173], v[48:51]
	v_mfma_f32_16x16x32_bf16 v[40:43], v[210:213], v[170:173], v[40:43]
	v_mfma_f32_16x16x32_bf16 v[32:35], v[202:205], v[178:181], v[32:35]
	v_mfma_f32_16x16x32_bf16 v[24:27], v[210:213], v[178:181], v[24:27]
	v_mfma_f32_16x16x32_bf16 v[16:19], v[202:205], v[186:189], v[16:19]
	v_mfma_f32_16x16x32_bf16 v[8:11], v[210:213], v[186:189], v[8:11]
	v_mfma_f32_16x16x32_bf16 v[4:7], v[202:205], v[194:197], v[4:7]
	v_mfma_f32_16x16x32_bf16 v[0:3], v[210:213], v[194:197], v[0:3]
	v_mfma_f32_16x16x32_bf16 v[48:51], v[206:209], v[174:177], v[48:51]
	v_mfma_f32_16x16x32_bf16 v[40:43], v[214:217], v[174:177], v[40:43]
	v_mfma_f32_16x16x32_bf16 v[32:35], v[206:209], v[182:185], v[32:35]
	v_mfma_f32_16x16x32_bf16 v[24:27], v[214:217], v[182:185], v[24:27]
	v_mfma_f32_16x16x32_bf16 v[16:19], v[206:209], v[190:193], v[16:19]
	v_mfma_f32_16x16x32_bf16 v[8:11], v[214:217], v[190:193], v[8:11]
	v_mfma_f32_16x16x32_bf16 v[4:7], v[206:209], v[198:201], v[4:7]
	v_mfma_f32_16x16x32_bf16 v[0:3], v[214:217], v[198:201], v[0:3]
	s_add_u32 s64, s64, 0x100
	s_addc_u32 s65, s65, 0
	s_add_u32 s31, s31, 0x100
	s_addc_u32 s57, s57, 0
	s_cmp_ge_i32 s85, s84
	s_mov_b32 s59, s85
	s_barrier
	s_cbranch_scc0 .LBB0_456
;     __device__ __forceinline__ void operator()(const f32x4 (&acc)[2][2][4][2], const Unit& u, int wr, int wc, int fr, int fq) const {
;         const int row0 = u.pm * BM + wr * 64 + fr, col0 = u.pn * BM + wc * 32 + 8 * fq;
;         if (u.part) {
;             float* base = tailacc + (size_t)(u.part - 1) * slab - (size_t)tail_row0 * tail_ld;
; #pragma unroll
;             for (int ai = 0; ai < 2; ++ai)
; #pragma unroll
;                 for (int m = 0; m < 4; ++m) { float* rowp = base + (size_t)(row0 + ai * HALF + m * 16) * tail_ld + col0;
; #pragma unroll
;                     for (int bj = 0; bj < 2; ++bj)
; #pragma unroll
;                         for (int n = 0; n < 2; ++n) *(f32x4*)(rowp + bj * HALF + 4 * n) = acc[ai][bj][m][n]; }
;             return;
	v_lshl_add_u32 v152, s8, 8, v155
	v_lshl_or_b32 v144, s30, 8, v157
	v_or_b32_e32 v150, 16, v152
	v_or_b32_e32 v148, 32, v152
	v_or_b32_e32 v146, 48, v152
	s_cmp_lg_u32 s81, 0
	v_ashrrev_i32_e32 v145, 31, v144
	v_ashrrev_i32_e32 v153, 31, v152
	v_ashrrev_i32_e32 v151, 31, v150
	v_ashrrev_i32_e32 v149, 31, v148
	v_ashrrev_i32_e32 v147, 31, v146
	s_cbranch_scc0 .LBB0_459
	s_add_i32 s8, s81, -1
	s_lshl_b64 s[30:31], s[8:9], 21
	s_add_u32 s30, s4, s30
	s_addc_u32 s31, s5, s31
	v_lshl_add_u64 v[162:163], v[144:145], 2, s[30:31]
	s_brev_b32 s30, 63
	s_mov_b32 s31, -1
	v_lshl_add_u64 v[162:163], v[162:163], 0, s[30:31]
	v_lshlrev_b64 v[164:165], 12, v[152:153]
	v_lshlrev_b64 v[166:167], 12, v[150:151]
	v_lshl_add_u64 v[164:165], v[162:163], 0, v[164:165]
	v_lshl_add_u64 v[166:167], v[162:163], 0, v[166:167]
	global_store_dwordx4 v[164:165], v[124:127], off
	global_store_dwordx4 v[164:165], v[120:123], off offset:16
	global_store_dwordx4 v[164:165], v[112:115], off offset:512
	global_store_dwordx4 v[164:165], v[104:107], off offset:528
	global_store_dwordx4 v[166:167], v[116:119], off
	global_store_dwordx4 v[166:167], v[108:111], off offset:16
	global_store_dwordx4 v[166:167], v[96:99], off offset:512
	global_store_dwordx4 v[166:167], v[88:91], off offset:528
	v_lshlrev_b64 v[166:167], 12, v[148:149]
	v_lshl_add_u64 v[166:167], v[162:163], 0, v[166:167]
	global_store_dwordx4 v[166:167], v[100:103], off
	global_store_dwordx4 v[166:167], v[92:95], off offset:16
	global_store_dwordx4 v[166:167], v[80:83], off offset:512
	global_store_dwordx4 v[166:167], v[72:75], off offset:528
	v_lshlrev_b64 v[166:167], 12, v[146:147]
	s_mov_b32 s8, 0x80000
	v_lshl_add_u64 v[162:163], v[162:163], 0, v[166:167]
	v_add_co_u32_e32 v166, vcc, s8, v164
	s_mov_b64 s[30:31], 0x80000
	s_nop 0
	v_addc_co_u32_e32 v167, vcc, 0, v165, vcc
	s_mov_b32 s8, 0x90000
	global_store_dwordx4 v[162:163], v[84:87], off
	global_store_dwordx4 v[162:163], v[76:79], off offset:16
	global_store_dwordx4 v[162:163], v[68:71], off offset:512
	global_store_dwordx4 v[162:163], v[64:67], off offset:528
	v_lshl_add_u64 v[162:163], v[164:165], 0, s[30:31]
	global_store_dwordx4 v[166:167], v[60:63], off
	global_store_dwordx4 v[162:163], v[56:59], off offset:16
	global_store_dwordx4 v[162:163], v[48:51], off offset:512
	global_store_dwordx4 v[162:163], v[40:43], off offset:528
	v_add_co_u32_e32 v166, vcc, s8, v164
	s_mov_b64 s[30:31], 0x90000
	s_nop 0
	v_addc_co_u32_e32 v167, vcc, 0, v165, vcc
	s_mov_b32 s8, 0xa0000
	v_lshl_add_u64 v[162:163], v[164:165], 0, s[30:31]
	global_store_dwordx4 v[166:167], v[52:55], off
	global_store_dwordx4 v[162:163], v[44:47], off offset:16
	global_store_dwordx4 v[162:163], v[32:35], off offset:512
	global_store_dwordx4 v[162:163], v[24:27], off offset:528
	s_mov_b64 s[30:31], 0xa0000
	v_add_co_u32_e32 v166, vcc, s8, v164
	v_lshl_add_u64 v[162:163], v[164:165], 0, s[30:31]
	s_nop 0
	v_addc_co_u32_e32 v167, vcc, 0, v165, vcc
	s_mov_b64 s[30:31], 0xb0000
	global_store_dwordx4 v[166:167], v[36:39], off
	global_store_dwordx4 v[162:163], v[28:31], off offset:16
	global_store_dwordx4 v[162:163], v[16:19], off offset:512
	global_store_dwordx4 v[162:163], v[8:11], off offset:528
	v_lshl_add_u64 v[162:163], v[164:165], 0, s[30:31]
	v_add_co_u32_e32 v164, vcc, 0xb0000, v164
	s_nop 1
	v_addc_co_u32_e32 v165, vcc, 0, v165, vcc
	global_store_dwordx4 v[164:165], v[20:23], off
	global_store_dwordx4 v[162:163], v[12:15], off offset:16
	global_store_dwordx4 v[162:163], v[4:7], off offset:512
	global_store_dwordx4 v[162:163], v[0:3], off offset:528
	s_cbranch_execnz .LBB0_441
	s_branch .LBB0_440

; #define PG8_STAGE(bufoff, gbase, voff) do { _Pragma("unroll") for (int _i = 0; _i < 2; ++_i) \
;         __builtin_amdgcn_global_load_lds((const unsigned*)((const char*)(gbase) + (voff)[_i]), (LAS unsigned*)(lds + (bufoff) + ldsw + _i * 8192), 16, 0, 0); } while (0)
; #define PG8_LDA(dst, b, h) do { _Pragma("unroll") for (int m = 0; m < 4; ++m) _Pragma("unroll") for (int k = 0; k < 2; ++k) dst[m][k] = *(const LAS bf16x8*)(lds + PG8_SA(b, h) + aoff + m * 2048 + k * 1024); } while (0)
; #define PG8_LDB(dst, b, h) do { _Pragma("unroll") for (int n = 0; n < 2; ++n) _Pragma("unroll") for (int k = 0; k < 2; ++k) dst[n][k] = *(const LAS bf16x8*)(lds + PG8_SB(b, h) + boff + n * 2048 + k * 1024); } while (0)
; #define PG8_MMA(ai, bj, At, Bt) do { __builtin_amdgcn_s_setprio(1); _Pragma("unroll") for (int m = 0; m < 4; ++m) _Pragma("unroll") for (int n = 0; n < 2; ++n) _Pragma("unroll") for (int k = 0; k < 2; ++k) \
;         acc[ai][bj][m][n] = __builtin_amdgcn_mfma_f32_16x16x32_bf16(Bt[n][k], At[m][k], acc[ai][bj][m][n], 0, 0, 0); __builtin_amdgcn_s_setprio(0); } while (0)
; #define PG8_WAIT_V(n) asm volatile("s_waitcnt vmcnt(" #n ")" ::: "memory")
; #define PG8_WAIT_L(n) asm volatile("s_waitcnt lgkmcnt(" #n ")" ::: "memory")
; template <class Epi>
; __device__ __forceinline__ void gemm_phase(LAS unsigned char* lds, const Gemm g, const StaticOrder& S, const Epi& E) {
;     ...
;         for (int t = 0; t < nt; t += 2) {
;             const bool last = (t == nt - 2);
;             const char* a1 = cA + (size_t)(t + 1) * kstep;
;             const char* a2 = last ? nA : cA + (size_t)(t + 2) * kstep; const char* b2 = last ? nB : cB + (size_t)(t + 2) * kstep;
;             const char* a3 = a2 + kstep; const char* b3 = b2 + kstep;
;             PG8_LDB(B0, 0, 0); PG8_SCHED; PG8_LDA(At, 0, 0); PG8_STAGE(PG8_SA(1, 1), a1 + hstepA, voffA);
;             PG8_WAIT_L(8); PG8_BAR; PG8_WAIT_L(0); PG8_MMA(0, 0, At, B0); PG8_BAR; PG8_SCHED;
;             PG8_LDB(B1, 0, 1); PG8_STAGE(PG8_SB(0, 0), b2, voffB);
;             PG8_BAR; PG8_WAIT_L(0); PG8_MMA(0, 1, At, B1); PG8_BAR;
;             PG8_LDA(At, 0, 1); PG8_STAGE(PG8_SA(0, 0), a2, voffA);
;             PG8_BAR; PG8_WAIT_L(0); PG8_MMA(1, 0, At, B0); PG8_BAR; PG8_SCHED;
;             PG8_STAGE(PG8_SB(0, 1), b2 + hstepB, voffB);
;             PG8_WAIT_V(6); PG8_BAR; PG8_MMA(1, 1, At, B1); PG8_BAR;
.LBB0_682:
	s_add_u32 s62, s60, 0xfffc0080
	s_addc_u32 s63, s61, -1
	s_cmp_eq_u32 s78, 12
	s_cselect_b32 s65, s41, s63
	s_cselect_b32 s64, s40, s62
	s_cselect_b32 s63, s57, s39
	s_cselect_b32 s62, s56, s37
	ds_read_b128 v[152:155], v159
	ds_read_b128 v[162:165], v159 offset:1024
	ds_read_b128 v[166:169], v159 offset:2048
	ds_read_b128 v[170:173], v159 offset:3072
	ds_read_b128 v[174:177], v160
	ds_read_b128 v[178:181], v160 offset:1024
	ds_read_b128 v[182:185], v160 offset:2048
	ds_read_b128 v[186:189], v160 offset:3072
	ds_read_b128 v[190:193], v160 offset:4096
	ds_read_b128 v[194:197], v160 offset:5120
	ds_read_b128 v[198:201], v160 offset:6144
	ds_read_b128 v[202:205], v160 offset:7168
	ds_read_b128 v[206:209], v161
	ds_read_b128 v[210:213], v161 offset:1024
	ds_read_b128 v[214:217], v161 offset:2048
	ds_read_b128 v[218:221], v161 offset:3072
	v_lshl_add_u64 v[242:243], s[60:61], 0, v[144:145]
	s_add_i32 m0, s35, 0xc000
	global_load_lds_dwordx4 v[242:243], off
	v_lshl_add_u64 v[242:243], s[60:61], 0, v[146:147]
	s_add_i32 m0, s35, 0xe000
	s_nop 0
	global_load_lds_dwordx4 v[242:243], off
	s_waitcnt vmcnt(8) lgkmcnt(0)
	s_barrier
	v_mfma_f32_16x16x32_bf16 v[124:127], v[152:155], v[174:177], v[124:127]
	v_mfma_f32_16x16x32_bf16 v[120:123], v[166:169], v[174:177], v[120:123]
	v_mfma_f32_16x16x32_bf16 v[116:119], v[152:155], v[182:185], v[116:119]
	v_mfma_f32_16x16x32_bf16 v[108:111], v[166:169], v[182:185], v[108:111]
	v_mfma_f32_16x16x32_bf16 v[100:103], v[152:155], v[190:193], v[100:103]
	v_mfma_f32_16x16x32_bf16 v[92:95], v[166:169], v[190:193], v[92:95]
	v_mfma_f32_16x16x32_bf16 v[84:87], v[152:155], v[198:201], v[84:87]
	v_mfma_f32_16x16x32_bf16 v[76:79], v[166:169], v[198:201], v[76:79]
	v_mfma_f32_16x16x32_bf16 v[124:127], v[162:165], v[178:181], v[124:127]
	v_mfma_f32_16x16x32_bf16 v[120:123], v[170:173], v[178:181], v[120:123]
	v_mfma_f32_16x16x32_bf16 v[116:119], v[162:165], v[186:189], v[116:119]
	v_mfma_f32_16x16x32_bf16 v[108:111], v[170:173], v[186:189], v[108:111]
	v_mfma_f32_16x16x32_bf16 v[100:103], v[162:165], v[194:197], v[100:103]
	v_mfma_f32_16x16x32_bf16 v[92:95], v[170:173], v[194:197], v[92:95]
	v_mfma_f32_16x16x32_bf16 v[84:87], v[162:165], v[202:205], v[84:87]
	v_mfma_f32_16x16x32_bf16 v[76:79], v[170:173], v[202:205], v[76:79]
	v_mfma_f32_16x16x32_bf16 v[112:115], v[206:209], v[174:177], v[112:115]
	v_mfma_f32_16x16x32_bf16 v[104:107], v[214:217], v[174:177], v[104:107]
	v_mfma_f32_16x16x32_bf16 v[96:99], v[206:209], v[182:185], v[96:99]
	v_mfma_f32_16x16x32_bf16 v[88:91], v[214:217], v[182:185], v[88:91]
	v_mfma_f32_16x16x32_bf16 v[80:83], v[206:209], v[190:193], v[80:83]
	v_mfma_f32_16x16x32_bf16 v[72:75], v[214:217], v[190:193], v[72:75]
	v_mfma_f32_16x16x32_bf16 v[68:71], v[206:209], v[198:201], v[68:71]
	v_mfma_f32_16x16x32_bf16 v[64:67], v[214:217], v[198:201], v[64:67]
	v_mfma_f32_16x16x32_bf16 v[112:115], v[210:213], v[178:181], v[112:115]
	v_mfma_f32_16x16x32_bf16 v[104:107], v[218:221], v[178:181], v[104:107]
	v_mfma_f32_16x16x32_bf16 v[96:99], v[210:213], v[186:189], v[96:99]
	v_mfma_f32_16x16x32_bf16 v[88:91], v[218:221], v[186:189], v[88:91]
	v_mfma_f32_16x16x32_bf16 v[80:83], v[210:213], v[194:197], v[80:83]
	v_mfma_f32_16x16x32_bf16 v[72:75], v[218:221], v[194:197], v[72:75]
	v_mfma_f32_16x16x32_bf16 v[68:71], v[210:213], v[202:205], v[68:71]
	v_mfma_f32_16x16x32_bf16 v[64:67], v[218:221], v[202:205], v[64:67]
	s_barrier
	ds_read_b128 v[174:177], v160 offset:16384
	ds_read_b128 v[178:181], v160 offset:17408
	ds_read_b128 v[182:185], v160 offset:18432
	ds_read_b128 v[186:189], v160 offset:19456
	ds_read_b128 v[190:193], v160 offset:20480
	ds_read_b128 v[194:197], v160 offset:21504
	ds_read_b128 v[198:201], v160 offset:22528
	ds_read_b128 v[202:205], v160 offset:23552
	s_add_i32 s79, s75, s33
	v_lshl_add_u64 v[222:223], s[62:63], 0, v[138:139]
	s_mov_b32 m0, s79
	global_load_lds_dwordx4 v[222:223], off
	v_lshl_add_u64 v[224:225], s[62:63], 0, v[142:143]
	s_add_i32 m0, s79, 0x2000
	s_nop 0
	global_load_lds_dwordx4 v[224:225], off
	s_mov_b32 m0, s35
	v_lshl_add_u64 v[226:227], s[64:65], 0, v[136:137]
	global_load_lds_dwordx4 v[226:227], off
	v_lshl_add_u64 v[228:229], s[64:65], 0, v[140:141]
	s_mov_b32 m0, s66
	s_nop 0
	global_load_lds_dwordx4 v[228:229], off
	s_add_u32 s80, s62, 0x40000
	s_addc_u32 s81, s63, 0
	s_add_i32 s79, s76, s33
	v_lshl_add_u64 v[240:241], s[80:81], 0, v[138:139]
	s_mov_b32 m0, s79
	s_nop 0
	global_load_lds_dwordx4 v[240:241], off
	v_lshl_add_u64 v[240:241], s[80:81], 0, v[142:143]
	s_add_i32 m0, s79, 0x2000
	s_nop 0
	global_load_lds_dwordx4 v[240:241], off
	s_waitcnt vmcnt(8) lgkmcnt(0)
	s_barrier
; #define PG8_STAGE(bufoff, gbase, voff) do { _Pragma("unroll") for (int _i = 0; _i < 2; ++_i) \
;         __builtin_amdgcn_global_load_lds((const unsigned*)((const char*)(gbase) + (voff)[_i]), (LAS unsigned*)(lds + (bufoff) + ldsw + _i * 8192), 16, 0, 0); } while (0)
; #define PG8_LDA(dst, b, h) do { _Pragma("unroll") for (int m = 0; m < 4; ++m) _Pragma("unroll") for (int k = 0; k < 2; ++k) dst[m][k] = *(const LAS bf16x8*)(lds + PG8_SA(b, h) + aoff + m * 2048 + k * 1024); } while (0)
; #define PG8_LDB(dst, b, h) do { _Pragma("unroll") for (int n = 0; n < 2; ++n) _Pragma("unroll") for (int k = 0; k < 2; ++k) dst[n][k] = *(const LAS bf16x8*)(lds + PG8_SB(b, h) + boff + n * 2048 + k * 1024); } while (0)
; #define PG8_MMA(ai, bj, At, Bt) do { __builtin_amdgcn_s_setprio(1); _Pragma("unroll") for (int m = 0; m < 4; ++m) _Pragma("unroll") for (int n = 0; n < 2; ++n) _Pragma("unroll") for (int k = 0; k < 2; ++k) \
;         acc[ai][bj][m][n] = __builtin_amdgcn_mfma_f32_16x16x32_bf16(Bt[n][k], At[m][k], acc[ai][bj][m][n], 0, 0, 0); __builtin_amdgcn_s_setprio(0); } while (0)
; #define PG8_WAIT_V(n) asm volatile("s_waitcnt vmcnt(" #n ")" ::: "memory")
; #define PG8_WAIT_L(n) asm volatile("s_waitcnt lgkmcnt(" #n ")" ::: "memory")
; #define PG8_BAR __builtin_amdgcn_s_barrier()
; #define PG8_SCHED __builtin_amdgcn_sched_barrier(0)
; template <class Epi>
; __device__ __forceinline__ void gemm_phase(LAS unsigned char* lds, const Gemm g, const StaticOrder& S, const Epi& E) {
;     ...
;             PG8_BAR; PG8_WAIT_L(0); PG8_MMA(1, 0, At, B0); PG8_BAR; PG8_SCHED;
;             PG8_STAGE(PG8_SB(0, 1), b2 + hstepB, voffB);
;             PG8_WAIT_V(6); PG8_BAR; PG8_MMA(1, 1, At, B1); PG8_BAR;
;             PG8_LDB(B0, 1, 0); PG8_SCHED; PG8_LDA(At, 1, 0); PG8_STAGE(PG8_SA(0, 1), a2 + hstepA, voffA);
;             PG8_WAIT_L(8); PG8_BAR; PG8_WAIT_L(0); PG8_MMA(0, 0, At, B0); PG8_BAR; PG8_SCHED;
;             PG8_LDB(B1, 1, 1); PG8_STAGE(PG8_SB(1, 0), b3, voffB);
;             PG8_BAR; PG8_WAIT_L(0); PG8_MMA(0, 1, At, B1); PG8_BAR;
	v_mfma_f32_16x16x32_bf16 v[60:63], v[152:155], v[174:177], v[60:63]
	v_mfma_f32_16x16x32_bf16 v[56:59], v[166:169], v[174:177], v[56:59]
	v_mfma_f32_16x16x32_bf16 v[52:55], v[152:155], v[182:185], v[52:55]
	v_mfma_f32_16x16x32_bf16 v[44:47], v[166:169], v[182:185], v[44:47]
	v_mfma_f32_16x16x32_bf16 v[36:39], v[152:155], v[190:193], v[36:39]
	v_mfma_f32_16x16x32_bf16 v[28:31], v[166:169], v[190:193], v[28:31]
	v_mfma_f32_16x16x32_bf16 v[20:23], v[152:155], v[198:201], v[20:23]
	v_mfma_f32_16x16x32_bf16 v[12:15], v[166:169], v[198:201], v[12:15]
	v_mfma_f32_16x16x32_bf16 v[60:63], v[162:165], v[178:181], v[60:63]
	v_mfma_f32_16x16x32_bf16 v[56:59], v[170:173], v[178:181], v[56:59]
	v_mfma_f32_16x16x32_bf16 v[52:55], v[162:165], v[186:189], v[52:55]
	v_mfma_f32_16x16x32_bf16 v[44:47], v[170:173], v[186:189], v[44:47]
	v_mfma_f32_16x16x32_bf16 v[36:39], v[162:165], v[194:197], v[36:39]
	v_mfma_f32_16x16x32_bf16 v[28:31], v[170:173], v[194:197], v[28:31]
	v_mfma_f32_16x16x32_bf16 v[20:23], v[162:165], v[202:205], v[20:23]
	v_mfma_f32_16x16x32_bf16 v[12:15], v[170:173], v[202:205], v[12:15]
	v_mfma_f32_16x16x32_bf16 v[48:51], v[206:209], v[174:177], v[48:51]
	v_mfma_f32_16x16x32_bf16 v[40:43], v[214:217], v[174:177], v[40:43]
	v_mfma_f32_16x16x32_bf16 v[32:35], v[206:209], v[182:185], v[32:35]
	v_mfma_f32_16x16x32_bf16 v[24:27], v[214:217], v[182:185], v[24:27]
	v_mfma_f32_16x16x32_bf16 v[16:19], v[206:209], v[190:193], v[16:19]
	v_mfma_f32_16x16x32_bf16 v[8:11], v[214:217], v[190:193], v[8:11]
	v_mfma_f32_16x16x32_bf16 v[4:7], v[206:209], v[198:201], v[4:7]
	v_mfma_f32_16x16x32_bf16 v[0:3], v[214:217], v[198:201], v[0:3]
	v_mfma_f32_16x16x32_bf16 v[48:51], v[210:213], v[178:181], v[48:51]
	v_mfma_f32_16x16x32_bf16 v[40:43], v[218:221], v[178:181], v[40:43]
	v_mfma_f32_16x16x32_bf16 v[32:35], v[210:213], v[186:189], v[32:35]
	v_mfma_f32_16x16x32_bf16 v[24:27], v[218:221], v[186:189], v[24:27]
	v_mfma_f32_16x16x32_bf16 v[16:19], v[210:213], v[194:197], v[16:19]
	v_mfma_f32_16x16x32_bf16 v[8:11], v[218:221], v[194:197], v[8:11]
	v_mfma_f32_16x16x32_bf16 v[4:7], v[210:213], v[202:205], v[4:7]
	v_mfma_f32_16x16x32_bf16 v[0:3], v[218:221], v[202:205], v[0:3]
	s_barrier
	s_add_i32 s79, 0, 0x18000
	v_add_u32_e32 v170, s79, v156
	ds_read_b128 v[152:155], v170
	ds_read_b128 v[162:165], v170 offset:1024
	ds_read_b128 v[166:169], v170 offset:2048
	ds_read_b128 v[170:173], v170 offset:3072
	ds_read_b128 v[174:177], v160 offset:32768
	ds_read_b128 v[178:181], v160 offset:33792
	ds_read_b128 v[182:185], v160 offset:34816
	ds_read_b128 v[186:189], v160 offset:35840
	ds_read_b128 v[190:193], v160 offset:36864
	ds_read_b128 v[194:197], v160 offset:37888
	ds_read_b128 v[198:201], v160 offset:38912
	ds_read_b128 v[202:205], v160 offset:39936
	s_add_i32 s98, 0, 0x1c000
	v_add_u32_e32 v218, s98, v156
	ds_read_b128 v[206:209], v218
	ds_read_b128 v[210:213], v218 offset:1024
	ds_read_b128 v[214:217], v218 offset:2048
	ds_read_b128 v[218:221], v218 offset:3072
	s_add_u32 s64, s64, 0x40000
	s_addc_u32 s65, s65, 0
	s_mov_b32 m0, s67
	v_lshl_add_u64 v[244:245], s[64:65], 0, v[136:137]
	global_load_lds_dwordx4 v[244:245], off
	v_lshl_add_u64 v[244:245], s[64:65], 0, v[140:141]
	s_mov_b32 m0, s68
	s_nop 0
	global_load_lds_dwordx4 v[244:245], off
	s_waitcnt vmcnt(8) lgkmcnt(0)
	s_barrier
	v_mfma_f32_16x16x32_bf16 v[124:127], v[152:155], v[174:177], v[124:127]
	v_mfma_f32_16x16x32_bf16 v[120:123], v[166:169], v[174:177], v[120:123]
	v_mfma_f32_16x16x32_bf16 v[116:119], v[152:155], v[182:185], v[116:119]
	v_mfma_f32_16x16x32_bf16 v[108:111], v[166:169], v[182:185], v[108:111]
	v_mfma_f32_16x16x32_bf16 v[100:103], v[152:155], v[190:193], v[100:103]
	v_mfma_f32_16x16x32_bf16 v[92:95], v[166:169], v[190:193], v[92:95]
	v_mfma_f32_16x16x32_bf16 v[84:87], v[152:155], v[198:201], v[84:87]
	v_mfma_f32_16x16x32_bf16 v[76:79], v[166:169], v[198:201], v[76:79]
	v_mfma_f32_16x16x32_bf16 v[124:127], v[162:165], v[178:181], v[124:127]
	v_mfma_f32_16x16x32_bf16 v[120:123], v[170:173], v[178:181], v[120:123]
	v_mfma_f32_16x16x32_bf16 v[116:119], v[162:165], v[186:189], v[116:119]
	v_mfma_f32_16x16x32_bf16 v[108:111], v[170:173], v[186:189], v[108:111]
	v_mfma_f32_16x16x32_bf16 v[100:103], v[162:165], v[194:197], v[100:103]
	v_mfma_f32_16x16x32_bf16 v[92:95], v[170:173], v[194:197], v[92:95]
	v_mfma_f32_16x16x32_bf16 v[84:87], v[162:165], v[202:205], v[84:87]
	v_mfma_f32_16x16x32_bf16 v[76:79], v[170:173], v[202:205], v[76:79]
	v_mfma_f32_16x16x32_bf16 v[112:115], v[206:209], v[174:177], v[112:115]
	v_mfma_f32_16x16x32_bf16 v[104:107], v[214:217], v[174:177], v[104:107]
	v_mfma_f32_16x16x32_bf16 v[96:99], v[206:209], v[182:185], v[96:99]
	v_mfma_f32_16x16x32_bf16 v[88:91], v[214:217], v[182:185], v[88:91]
	v_mfma_f32_16x16x32_bf16 v[80:83], v[206:209], v[190:193], v[80:83]
	v_mfma_f32_16x16x32_bf16 v[72:75], v[214:217], v[190:193], v[72:75]
	v_mfma_f32_16x16x32_bf16 v[68:71], v[206:209], v[198:201], v[68:71]
	v_mfma_f32_16x16x32_bf16 v[64:67], v[214:217], v[198:201], v[64:67]
	v_mfma_f32_16x16x32_bf16 v[112:115], v[210:213], v[178:181], v[112:115]
	v_mfma_f32_16x16x32_bf16 v[104:107], v[218:221], v[178:181], v[104:107]
	v_mfma_f32_16x16x32_bf16 v[96:99], v[210:213], v[186:189], v[96:99]
	v_mfma_f32_16x16x32_bf16 v[88:91], v[218:221], v[186:189], v[88:91]
	v_mfma_f32_16x16x32_bf16 v[80:83], v[210:213], v[194:197], v[80:83]
	v_mfma_f32_16x16x32_bf16 v[72:75], v[218:221], v[194:197], v[72:75]
	v_mfma_f32_16x16x32_bf16 v[68:71], v[210:213], v[202:205], v[68:71]
	v_mfma_f32_16x16x32_bf16 v[64:67], v[218:221], v[202:205], v[64:67]
	s_barrier
; __device__ __forceinline__ unsigned pk2(float lo, float hi) { unsigned r; asm("v_cvt_pk_bf16_f32 %0, %1, %2" : "=v"(r) : "v"(lo), "v"(hi)); return r; }
; __device__ __forceinline__ float gelu_t(float x) { return x * __builtin_amdgcn_rcpf(1.f + __expf(-1.5957691216057308f * (x + 0.044715f * x * x * x))); }
; #define PG8_STAGE(bufoff, gbase, voff) do { _Pragma("unroll") for (int _i = 0; _i < 2; ++_i) \
;         __builtin_amdgcn_global_load_lds((const unsigned*)((const char*)(gbase) + (voff)[_i]), (LAS unsigned*)(lds + (bufoff) + ldsw + _i * 8192), 16, 0, 0); } while (0)
; #define PG8_LDA(dst, b, h) do { _Pragma("unroll") for (int m = 0; m < 4; ++m) _Pragma("unroll") for (int k = 0; k < 2; ++k) dst[m][k] = *(const LAS bf16x8*)(lds + PG8_SA(b, h) + aoff + m * 2048 + k * 1024); } while (0)
;     __device__ __forceinline__ void operator()(const f32x4 (&acc)[2][2][4][2], const Unit& u, int wr, int wc, int fr, int fq) const {
;     ...
; #pragma unroll
;         for (int ai = 0; ai < 2; ++ai)
; #pragma unroll
;             for (int m = 0; m < 4; ++m) { const int row = row0 + ai * HALF + m * 16; u16* rowp = O + (size_t)row * ldc + col0;
; #pragma unroll
;                 for (int bj = 0; bj < 2; ++bj) { f32x4 v0 = acc[ai][bj][m][0], v1 = acc[ai][bj][m][1];
;                     if (col0 + bj * HALF >= gelu_from) { v0 = (f32x4){gelu_t(v0.x), gelu_t(v0.y), gelu_t(v0.z), gelu_t(v0.w)}; v1 = (f32x4){gelu_t(v1.x), gelu_t(v1.y), gelu_t(v1.z), gelu_t(v1.w)}; }
;                     u32x4 w; w.x = pk2(v0[0], v0[1]); w.y = pk2(v0[2], v0[3]); w.z = pk2(v1[0], v1[1]); w.w = pk2(v1[2], v1[3]);
;                     *(u32x4*)(rowp + bj * HALF) = w;
;                     if (halo != nullptr && m == 3 && fr >= 14) *(u32x4*)(halo + (size_t)((row >> 6) * 2 + (fr - 14)) * ldc + col0 + bj * HALF) = w; } }
; template <class Epi>
; __device__ __forceinline__ void gemm_phase(LAS unsigned char* lds, const Gemm g, const StaticOrder& S, const Epi& E) {
;     ...
;             PG8_LDB(B1, 1, 1); PG8_STAGE(PG8_SB(1, 0), b3, voffB);
;             PG8_BAR; PG8_WAIT_L(0); PG8_MMA(0, 1, At, B1); PG8_BAR;
;             PG8_LDA(At, 1, 1); PG8_STAGE(PG8_SA(1, 0), a3, voffA);
;             PG8_BAR; PG8_WAIT_L(0); PG8_MMA(1, 0, At, B0); PG8_BAR; PG8_SCHED;
;             PG8_STAGE(PG8_SB(1, 1), b3 + hstepB, voffB);
;             PG8_WAIT_V(6); PG8_BAR; PG8_MMA(1, 1, At, B1); PG8_BAR;
	ds_read_b128 v[174:177], v160 offset:49152
	ds_read_b128 v[178:181], v160 offset:50176
	ds_read_b128 v[182:185], v160 offset:51200
	ds_read_b128 v[186:189], v160 offset:52224
	ds_read_b128 v[190:193], v160 offset:53248
	ds_read_b128 v[194:197], v160 offset:54272
	ds_read_b128 v[198:201], v160 offset:55296
	ds_read_b128 v[202:205], v160 offset:56320
	s_add_i32 s65, s79, s33
	v_lshl_add_u64 v[222:223], v[222:223], 0, s[28:29]
	s_mov_b32 m0, s65
	global_load_lds_dwordx4 v[222:223], off
	v_lshl_add_u64 v[222:223], v[224:225], 0, s[28:29]
	s_add_i32 m0, s65, 0x2000
	s_nop 0
	global_load_lds_dwordx4 v[222:223], off
	s_mov_b32 m0, s71
	v_lshl_add_u64 v[222:223], v[226:227], 0, s[28:29]
	global_load_lds_dwordx4 v[222:223], off
	v_lshl_add_u64 v[222:223], v[228:229], 0, s[28:29]
	s_mov_b32 m0, s72
	s_nop 0
	global_load_lds_dwordx4 v[222:223], off
	s_add_u32 s62, s62, 0x40080
	s_addc_u32 s63, s63, 0
	s_add_i32 s64, s98, s33
	v_lshl_add_u64 v[240:241], s[62:63], 0, v[138:139]
	s_mov_b32 m0, s64
	s_nop 0
	global_load_lds_dwordx4 v[240:241], off
	v_lshl_add_u64 v[240:241], s[62:63], 0, v[142:143]
	s_add_i32 m0, s64, 0x2000
	s_nop 0
	global_load_lds_dwordx4 v[240:241], off
	s_waitcnt vmcnt(8) lgkmcnt(0)
	s_barrier
	v_mfma_f32_16x16x32_bf16 v[60:63], v[152:155], v[174:177], v[60:63]
	v_mfma_f32_16x16x32_bf16 v[56:59], v[166:169], v[174:177], v[56:59]
	v_mfma_f32_16x16x32_bf16 v[52:55], v[152:155], v[182:185], v[52:55]
	v_mfma_f32_16x16x32_bf16 v[44:47], v[166:169], v[182:185], v[44:47]
	v_mfma_f32_16x16x32_bf16 v[36:39], v[152:155], v[190:193], v[36:39]
	v_mfma_f32_16x16x32_bf16 v[28:31], v[166:169], v[190:193], v[28:31]
	v_mfma_f32_16x16x32_bf16 v[20:23], v[152:155], v[198:201], v[20:23]
	v_mfma_f32_16x16x32_bf16 v[12:15], v[166:169], v[198:201], v[12:15]
	v_mfma_f32_16x16x32_bf16 v[60:63], v[162:165], v[178:181], v[60:63]
	v_mfma_f32_16x16x32_bf16 v[56:59], v[170:173], v[178:181], v[56:59]
	v_mfma_f32_16x16x32_bf16 v[52:55], v[162:165], v[186:189], v[52:55]
	v_mfma_f32_16x16x32_bf16 v[44:47], v[170:173], v[186:189], v[44:47]
	v_mfma_f32_16x16x32_bf16 v[36:39], v[162:165], v[194:197], v[36:39]
	v_mfma_f32_16x16x32_bf16 v[28:31], v[170:173], v[194:197], v[28:31]
	v_mfma_f32_16x16x32_bf16 v[20:23], v[162:165], v[202:205], v[20:23]
	v_mfma_f32_16x16x32_bf16 v[12:15], v[170:173], v[202:205], v[12:15]
	v_mfma_f32_16x16x32_bf16 v[48:51], v[206:209], v[174:177], v[48:51]
	v_mfma_f32_16x16x32_bf16 v[40:43], v[214:217], v[174:177], v[40:43]
	v_mfma_f32_16x16x32_bf16 v[32:35], v[206:209], v[182:185], v[32:35]
	v_mfma_f32_16x16x32_bf16 v[24:27], v[214:217], v[182:185], v[24:27]
	v_mfma_f32_16x16x32_bf16 v[16:19], v[206:209], v[190:193], v[16:19]
	v_mfma_f32_16x16x32_bf16 v[8:11], v[214:217], v[190:193], v[8:11]
	v_mfma_f32_16x16x32_bf16 v[4:7], v[206:209], v[198:201], v[4:7]
	v_mfma_f32_16x16x32_bf16 v[0:3], v[214:217], v[198:201], v[0:3]
	v_mfma_f32_16x16x32_bf16 v[48:51], v[210:213], v[178:181], v[48:51]
	v_mfma_f32_16x16x32_bf16 v[40:43], v[218:221], v[178:181], v[40:43]
	v_mfma_f32_16x16x32_bf16 v[32:35], v[210:213], v[186:189], v[32:35]
	v_mfma_f32_16x16x32_bf16 v[24:27], v[218:221], v[186:189], v[24:27]
	v_mfma_f32_16x16x32_bf16 v[16:19], v[210:213], v[194:197], v[16:19]
	v_mfma_f32_16x16x32_bf16 v[8:11], v[218:221], v[194:197], v[8:11]
	v_mfma_f32_16x16x32_bf16 v[4:7], v[210:213], v[202:205], v[4:7]
	v_mfma_f32_16x16x32_bf16 v[0:3], v[218:221], v[202:205], v[0:3]
	s_add_i32 s78, s78, 2
	s_add_u32 s60, s60, 0x100
	s_addc_u32 s61, s61, 0
	s_add_u32 s37, s37, 0x100
	s_addc_u32 s39, s39, 0
	s_cmp_gt_u32 s78, 13
	s_barrier
	s_cbranch_scc0 .LBB0_682
	s_lshl_b32 s37, s58, 8
	s_add_i32 s37, s37, s70
	v_lshl_or_b32 v152, s59, 8, v158
	v_or_b32_e32 v162, s37, v135
	v_ashrrev_i32_e32 v153, 31, v152
	v_mov_b64_e32 v[164:165], s[4:5]
	v_mad_i64_i32 v[166:167], s[58:59], v162, s77, v[164:165]
	v_lshlrev_b64 v[154:155], 1, v[152:153]
	v_cvt_pk_bf16_f32 v112, v112, v113
	v_cvt_pk_bf16_f32 v113, v114, v115
	v_cvt_pk_bf16_f32 v114, v104, v105
	v_or_b32_e32 v104, 16, v162
	v_lshl_add_u64 v[166:167], v[166:167], 0, v[154:155]
	v_mad_i64_i32 v[104:105], s[58:59], v104, s77, v[164:165]
	v_cvt_pk_bf16_f32 v96, v96, v97
	v_cvt_pk_bf16_f32 v97, v98, v99
	v_cvt_pk_bf16_f32 v98, v88, v89
	v_or_b32_e32 v88, 32, v162
	v_cvt_pk_bf16_f32 v115, v106, v107
	global_store_dwordx4 v[166:167], v[112:115], off offset:256
	v_mad_i64_i32 v[88:89], s[58:59], v88, s77, v[164:165]
	s_nop 0
	v_lshl_add_u64 v[112:113], v[104:105], 0, v[154:155]
	v_cvt_pk_bf16_f32 v80, v80, v81
	v_cvt_pk_bf16_f32 v81, v82, v83
	v_cvt_pk_bf16_f32 v82, v72, v73
	v_or_b32_e32 v72, 48, v162
	s_ashr_i32 s37, s37, 5
	v_cvt_pk_bf16_f32 v99, v90, v91
	global_store_dwordx4 v[112:113], v[96:99], off offset:256
	v_mad_i64_i32 v[72:73], s[58:59], v72, s77, v[164:165]
	s_nop 0
	v_lshl_add_u64 v[96:97], v[88:89], 0, v[154:155]
	v_add_u32_e32 v163, s37, v157
	v_cvt_pk_bf16_f32 v83, v74, v75
	global_store_dwordx4 v[96:97], v[80:83], off offset:256
	v_cvt_pk_bf16_f32 v124, v124, v125
	v_cvt_pk_bf16_f32 v125, v126, v127
	v_cvt_pk_bf16_f32 v126, v120, v121
	v_cvt_pk_bf16_f32 v127, v122, v123
	global_store_dwordx4 v[166:167], v[124:127], off
	s_nop 0
	v_lshl_add_u64 v[80:81], v[72:73], 0, v[154:155]
	v_cvt_pk_bf16_f32 v104, v116, v117
	v_cvt_pk_bf16_f32 v105, v118, v119
	v_cvt_pk_bf16_f32 v106, v108, v109
	v_cvt_pk_bf16_f32 v107, v110, v111
	global_store_dwordx4 v[112:113], v[104:107], off
	v_cvt_pk_bf16_f32 v88, v100, v101
	v_cvt_pk_bf16_f32 v89, v102, v103
	v_cvt_pk_bf16_f32 v90, v92, v93
	v_cvt_pk_bf16_f32 v91, v94, v95
	global_store_dwordx4 v[96:97], v[88:91], off
	v_cvt_pk_bf16_f32 v72, v84, v85
	v_cvt_pk_bf16_f32 v73, v86, v87
	v_cvt_pk_bf16_f32 v74, v76, v77
	v_cvt_pk_bf16_f32 v75, v78, v79
	global_store_dwordx4 v[80:81], v[72:75], off
	s_and_saveexec_b64 s[58:59], s[0:1]
	s_cbranch_execz .LBB0_685
	v_mov_b64_e32 v[76:77], s[18:19]
	v_mad_i64_i32 v[76:77], s[60:61], v163, s77, v[76:77]
	v_lshl_add_u64 v[76:77], v[152:153], 1, v[76:77]
	global_store_dwordx4 v[76:77], v[72:75], off

; #define PG8_STAGE(bufoff, gbase, voff) do { _Pragma("unroll") for (int _i = 0; _i < 2; ++_i) \
;         __builtin_amdgcn_global_load_lds((const unsigned*)((const char*)(gbase) + (voff)[_i]), (LAS unsigned*)(lds + (bufoff) + ldsw + _i * 8192), 16, 0, 0); } while (0)
; #define PG8_LDA(dst, b, h) do { _Pragma("unroll") for (int m = 0; m < 4; ++m) _Pragma("unroll") for (int k = 0; k < 2; ++k) dst[m][k] = *(const LAS bf16x8*)(lds + PG8_SA(b, h) + aoff + m * 2048 + k * 1024); } while (0)
; #define PG8_LDB(dst, b, h) do { _Pragma("unroll") for (int n = 0; n < 2; ++n) _Pragma("unroll") for (int k = 0; k < 2; ++k) dst[n][k] = *(const LAS bf16x8*)(lds + PG8_SB(b, h) + boff + n * 2048 + k * 1024); } while (0)
; #define PG8_MMA(ai, bj, At, Bt) do { __builtin_amdgcn_s_setprio(1); _Pragma("unroll") for (int m = 0; m < 4; ++m) _Pragma("unroll") for (int n = 0; n < 2; ++n) _Pragma("unroll") for (int k = 0; k < 2; ++k) \
;         acc[ai][bj][m][n] = __builtin_amdgcn_mfma_f32_16x16x32_bf16(Bt[n][k], At[m][k], acc[ai][bj][m][n], 0, 0, 0); __builtin_amdgcn_s_setprio(0); } while (0)
; #define PG8_WAIT_V(n) asm volatile("s_waitcnt vmcnt(" #n ")" ::: "memory")
; #define PG8_WAIT_L(n) asm volatile("s_waitcnt lgkmcnt(" #n ")" ::: "memory")
; template <class Epi>
; __device__ __forceinline__ void gemm_phase(LAS unsigned char* lds, const Gemm g, const StaticOrder& S, const Epi& E) {
;     ...
;         for (int t = 0; t < nt; t += 2) {
;             const bool last = (t == nt - 2);
;             const char* a1 = cA + (size_t)(t + 1) * kstep;
;             const char* a2 = last ? nA : cA + (size_t)(t + 2) * kstep; const char* b2 = last ? nB : cB + (size_t)(t + 2) * kstep;
;             const char* a3 = a2 + kstep; const char* b3 = b2 + kstep;
;             PG8_LDB(B0, 0, 0); PG8_SCHED; PG8_LDA(At, 0, 0); PG8_STAGE(PG8_SA(1, 1), a1 + hstepA, voffA);
;             PG8_WAIT_L(8); PG8_BAR; PG8_WAIT_L(0); PG8_MMA(0, 0, At, B0); PG8_BAR; PG8_SCHED;
;             PG8_LDB(B1, 0, 1); PG8_STAGE(PG8_SB(0, 0), b2, voffB);
;             PG8_BAR; PG8_WAIT_L(0); PG8_MMA(0, 1, At, B1); PG8_BAR;
;             PG8_LDA(At, 0, 1); PG8_STAGE(PG8_SA(0, 0), a2, voffA);
;             PG8_BAR; PG8_WAIT_L(0); PG8_MMA(1, 0, At, B0); PG8_BAR; PG8_SCHED;
;             PG8_STAGE(PG8_SB(0, 1), b2 + hstepB, voffB);
;             PG8_WAIT_V(6); PG8_BAR; PG8_MMA(1, 1, At, B1); PG8_BAR;
.LBB0_910:
	s_add_i32 s83, s54, 2
	s_add_u32 s55, s46, 0xffea0080
	s_addc_u32 s56, s47, -1
	s_cmp_eq_u32 s18, s54
	s_cselect_b32 s54, s0, s41
	s_cselect_b32 s57, s45, s56
	s_cselect_b32 s56, s44, s55
	s_cselect_b32 s55, s1, s82
	ds_read_b128 v[150:153], v170
	ds_read_b128 v[154:157], v170 offset:1024
	ds_read_b128 v[174:177], v170 offset:2048
	ds_read_b128 v[178:181], v170 offset:3072
	ds_read_b128 v[182:185], v171
	ds_read_b128 v[186:189], v171 offset:1024
	ds_read_b128 v[190:193], v171 offset:2048
	ds_read_b128 v[194:197], v171 offset:3072
	ds_read_b128 v[198:201], v171 offset:4096
	ds_read_b128 v[202:205], v171 offset:5120
	ds_read_b128 v[206:209], v171 offset:6144
	ds_read_b128 v[210:213], v171 offset:7168
	ds_read_b128 v[214:217], v172
	ds_read_b128 v[218:221], v172 offset:1024
	ds_read_b128 v[222:225], v172 offset:2048
	ds_read_b128 v[226:229], v172 offset:3072
	v_lshl_add_u64 v[158:159], s[46:47], 0, v[144:145]
	s_add_i32 m0, s33, 0xc000
	global_load_lds_dwordx4 v[158:159], off
	v_lshl_add_u64 v[158:159], s[46:47], 0, v[146:147]
	s_add_i32 m0, s33, 0xe000
	s_nop 0
	global_load_lds_dwordx4 v[158:159], off
	s_waitcnt vmcnt(8) lgkmcnt(0)
	s_barrier
	v_mfma_f32_16x16x32_bf16 v[124:127], v[150:153], v[182:185], v[124:127]
	v_mfma_f32_16x16x32_bf16 v[120:123], v[174:177], v[182:185], v[120:123]
	v_mfma_f32_16x16x32_bf16 v[116:119], v[150:153], v[190:193], v[116:119]
	v_mfma_f32_16x16x32_bf16 v[108:111], v[174:177], v[190:193], v[108:111]
	v_mfma_f32_16x16x32_bf16 v[100:103], v[150:153], v[198:201], v[100:103]
	v_mfma_f32_16x16x32_bf16 v[92:95], v[174:177], v[198:201], v[92:95]
	v_mfma_f32_16x16x32_bf16 v[84:87], v[150:153], v[206:209], v[84:87]
	v_mfma_f32_16x16x32_bf16 v[76:79], v[174:177], v[206:209], v[76:79]
	v_mfma_f32_16x16x32_bf16 v[124:127], v[154:157], v[186:189], v[124:127]
	v_mfma_f32_16x16x32_bf16 v[120:123], v[178:181], v[186:189], v[120:123]
	v_mfma_f32_16x16x32_bf16 v[116:119], v[154:157], v[194:197], v[116:119]
	v_mfma_f32_16x16x32_bf16 v[108:111], v[178:181], v[194:197], v[108:111]
	v_mfma_f32_16x16x32_bf16 v[100:103], v[154:157], v[202:205], v[100:103]
	v_mfma_f32_16x16x32_bf16 v[92:95], v[178:181], v[202:205], v[92:95]
	v_mfma_f32_16x16x32_bf16 v[84:87], v[154:157], v[210:213], v[84:87]
	v_mfma_f32_16x16x32_bf16 v[76:79], v[178:181], v[210:213], v[76:79]
	v_mfma_f32_16x16x32_bf16 v[112:115], v[214:217], v[182:185], v[112:115]
	v_mfma_f32_16x16x32_bf16 v[104:107], v[222:225], v[182:185], v[104:107]
	v_mfma_f32_16x16x32_bf16 v[96:99], v[214:217], v[190:193], v[96:99]
	v_mfma_f32_16x16x32_bf16 v[88:91], v[222:225], v[190:193], v[88:91]
	v_mfma_f32_16x16x32_bf16 v[80:83], v[214:217], v[198:201], v[80:83]
	v_mfma_f32_16x16x32_bf16 v[72:75], v[222:225], v[198:201], v[72:75]
	v_mfma_f32_16x16x32_bf16 v[68:71], v[214:217], v[206:209], v[68:71]
	v_mfma_f32_16x16x32_bf16 v[64:67], v[222:225], v[206:209], v[64:67]
	v_mfma_f32_16x16x32_bf16 v[112:115], v[218:221], v[186:189], v[112:115]
	v_mfma_f32_16x16x32_bf16 v[104:107], v[226:229], v[186:189], v[104:107]
	v_mfma_f32_16x16x32_bf16 v[96:99], v[218:221], v[194:197], v[96:99]
	v_mfma_f32_16x16x32_bf16 v[88:91], v[226:229], v[194:197], v[88:91]
	v_mfma_f32_16x16x32_bf16 v[80:83], v[218:221], v[202:205], v[80:83]
	v_mfma_f32_16x16x32_bf16 v[72:75], v[226:229], v[202:205], v[72:75]
	v_mfma_f32_16x16x32_bf16 v[68:71], v[218:221], v[210:213], v[68:71]
	v_mfma_f32_16x16x32_bf16 v[64:67], v[226:229], v[210:213], v[64:67]
	s_barrier
	ds_read_b128 v[182:185], v171 offset:16384
	ds_read_b128 v[186:189], v171 offset:17408
	ds_read_b128 v[190:193], v171 offset:18432
	ds_read_b128 v[194:197], v171 offset:19456
	ds_read_b128 v[198:201], v171 offset:20480
	ds_read_b128 v[202:205], v171 offset:21504
	ds_read_b128 v[206:209], v171 offset:22528
	ds_read_b128 v[210:213], v171 offset:23552
	s_add_i32 s84, s65, s21
	v_lshl_add_u64 v[158:159], s[54:55], 0, v[138:139]
	s_mov_b32 m0, s84
	global_load_lds_dwordx4 v[158:159], off
	v_lshl_add_u64 v[230:231], s[54:55], 0, v[142:143]
	s_add_i32 m0, s84, 0x2000
	s_nop 0
	global_load_lds_dwordx4 v[230:231], off
	s_mov_b32 m0, s33
	v_lshl_add_u64 v[232:233], s[56:57], 0, v[136:137]
	global_load_lds_dwordx4 v[232:233], off
	v_lshl_add_u64 v[234:235], s[56:57], 0, v[140:141]
	s_mov_b32 m0, s35
	s_nop 0
	global_load_lds_dwordx4 v[234:235], off
	s_add_u32 s84, s54, 0xb0000
	s_addc_u32 s85, s55, 0
	s_add_i32 s86, s66, s21
	v_lshl_add_u64 v[240:241], s[84:85], 0, v[138:139]
	s_mov_b32 m0, s86
	s_nop 0
	global_load_lds_dwordx4 v[240:241], off
	v_lshl_add_u64 v[240:241], s[84:85], 0, v[142:143]
	s_add_i32 m0, s86, 0x2000
	s_nop 0
	global_load_lds_dwordx4 v[240:241], off
	s_waitcnt vmcnt(8) lgkmcnt(0)
	s_barrier
; #define PG8_STAGE(bufoff, gbase, voff) do { _Pragma("unroll") for (int _i = 0; _i < 2; ++_i) \
;         __builtin_amdgcn_global_load_lds((const unsigned*)((const char*)(gbase) + (voff)[_i]), (LAS unsigned*)(lds + (bufoff) + ldsw + _i * 8192), 16, 0, 0); } while (0)
; #define PG8_LDA(dst, b, h) do { _Pragma("unroll") for (int m = 0; m < 4; ++m) _Pragma("unroll") for (int k = 0; k < 2; ++k) dst[m][k] = *(const LAS bf16x8*)(lds + PG8_SA(b, h) + aoff + m * 2048 + k * 1024); } while (0)
; #define PG8_LDB(dst, b, h) do { _Pragma("unroll") for (int n = 0; n < 2; ++n) _Pragma("unroll") for (int k = 0; k < 2; ++k) dst[n][k] = *(const LAS bf16x8*)(lds + PG8_SB(b, h) + boff + n * 2048 + k * 1024); } while (0)
; #define PG8_MMA(ai, bj, At, Bt) do { __builtin_amdgcn_s_setprio(1); _Pragma("unroll") for (int m = 0; m < 4; ++m) _Pragma("unroll") for (int n = 0; n < 2; ++n) _Pragma("unroll") for (int k = 0; k < 2; ++k) \
;         acc[ai][bj][m][n] = __builtin_amdgcn_mfma_f32_16x16x32_bf16(Bt[n][k], At[m][k], acc[ai][bj][m][n], 0, 0, 0); __builtin_amdgcn_s_setprio(0); } while (0)
; #define PG8_WAIT_V(n) asm volatile("s_waitcnt vmcnt(" #n ")" ::: "memory")
; #define PG8_WAIT_L(n) asm volatile("s_waitcnt lgkmcnt(" #n ")" ::: "memory")
; #define PG8_BAR __builtin_amdgcn_s_barrier()
; #define PG8_SCHED __builtin_amdgcn_sched_barrier(0)
; template <class Epi>
; __device__ __forceinline__ void gemm_phase(LAS unsigned char* lds, const Gemm g, const StaticOrder& S, const Epi& E) {
;     ...
;             PG8_BAR; PG8_WAIT_L(0); PG8_MMA(1, 0, At, B0); PG8_BAR; PG8_SCHED;
;             PG8_STAGE(PG8_SB(0, 1), b2 + hstepB, voffB);
;             PG8_WAIT_V(6); PG8_BAR; PG8_MMA(1, 1, At, B1); PG8_BAR;
;             PG8_LDB(B0, 1, 0); PG8_SCHED; PG8_LDA(At, 1, 0); PG8_STAGE(PG8_SA(0, 1), a2 + hstepA, voffA);
;             PG8_WAIT_L(8); PG8_BAR; PG8_WAIT_L(0); PG8_MMA(0, 0, At, B0); PG8_BAR; PG8_SCHED;
;             PG8_LDB(B1, 1, 1); PG8_STAGE(PG8_SB(1, 0), b3, voffB);
;             PG8_BAR; PG8_WAIT_L(0); PG8_MMA(0, 1, At, B1); PG8_BAR;
	v_mfma_f32_16x16x32_bf16 v[60:63], v[150:153], v[182:185], v[60:63]
	v_mfma_f32_16x16x32_bf16 v[56:59], v[174:177], v[182:185], v[56:59]
	v_mfma_f32_16x16x32_bf16 v[52:55], v[150:153], v[190:193], v[52:55]
	v_mfma_f32_16x16x32_bf16 v[44:47], v[174:177], v[190:193], v[44:47]
	v_mfma_f32_16x16x32_bf16 v[36:39], v[150:153], v[198:201], v[36:39]
	v_mfma_f32_16x16x32_bf16 v[28:31], v[174:177], v[198:201], v[28:31]
	v_mfma_f32_16x16x32_bf16 v[20:23], v[150:153], v[206:209], v[20:23]
	v_mfma_f32_16x16x32_bf16 v[12:15], v[174:177], v[206:209], v[12:15]
	v_mfma_f32_16x16x32_bf16 v[60:63], v[154:157], v[186:189], v[60:63]
	v_mfma_f32_16x16x32_bf16 v[56:59], v[178:181], v[186:189], v[56:59]
	v_mfma_f32_16x16x32_bf16 v[52:55], v[154:157], v[194:197], v[52:55]
	v_mfma_f32_16x16x32_bf16 v[44:47], v[178:181], v[194:197], v[44:47]
	v_mfma_f32_16x16x32_bf16 v[36:39], v[154:157], v[202:205], v[36:39]
	v_mfma_f32_16x16x32_bf16 v[28:31], v[178:181], v[202:205], v[28:31]
	v_mfma_f32_16x16x32_bf16 v[20:23], v[154:157], v[210:213], v[20:23]
	v_mfma_f32_16x16x32_bf16 v[12:15], v[178:181], v[210:213], v[12:15]
	v_mfma_f32_16x16x32_bf16 v[48:51], v[214:217], v[182:185], v[48:51]
	v_mfma_f32_16x16x32_bf16 v[40:43], v[222:225], v[182:185], v[40:43]
	v_mfma_f32_16x16x32_bf16 v[32:35], v[214:217], v[190:193], v[32:35]
	v_mfma_f32_16x16x32_bf16 v[24:27], v[222:225], v[190:193], v[24:27]
	v_mfma_f32_16x16x32_bf16 v[16:19], v[214:217], v[198:201], v[16:19]
	v_mfma_f32_16x16x32_bf16 v[8:11], v[222:225], v[198:201], v[8:11]
	v_mfma_f32_16x16x32_bf16 v[4:7], v[214:217], v[206:209], v[4:7]
	v_mfma_f32_16x16x32_bf16 v[0:3], v[222:225], v[206:209], v[0:3]
	v_mfma_f32_16x16x32_bf16 v[48:51], v[218:221], v[186:189], v[48:51]
	v_mfma_f32_16x16x32_bf16 v[40:43], v[226:229], v[186:189], v[40:43]
	v_mfma_f32_16x16x32_bf16 v[32:35], v[218:221], v[194:197], v[32:35]
	v_mfma_f32_16x16x32_bf16 v[24:27], v[226:229], v[194:197], v[24:27]
	v_mfma_f32_16x16x32_bf16 v[16:19], v[218:221], v[202:205], v[16:19]
	v_mfma_f32_16x16x32_bf16 v[8:11], v[226:229], v[202:205], v[8:11]
	v_mfma_f32_16x16x32_bf16 v[4:7], v[218:221], v[210:213], v[4:7]
	v_mfma_f32_16x16x32_bf16 v[0:3], v[226:229], v[210:213], v[0:3]
	s_barrier
	s_add_i32 s84, 0, 0x18000
	v_add_u32_e32 v173, s84, v168
	ds_read_b128 v[150:153], v173
	ds_read_b128 v[154:157], v173 offset:1024
	ds_read_b128 v[174:177], v173 offset:2048
	ds_read_b128 v[178:181], v173 offset:3072
	ds_read_b128 v[182:185], v171 offset:32768
	ds_read_b128 v[186:189], v171 offset:33792
	ds_read_b128 v[190:193], v171 offset:34816
	ds_read_b128 v[194:197], v171 offset:35840
	ds_read_b128 v[198:201], v171 offset:36864
	ds_read_b128 v[202:205], v171 offset:37888
	ds_read_b128 v[206:209], v171 offset:38912
	ds_read_b128 v[210:213], v171 offset:39936
	s_add_i32 s98, 0, 0x1c000
	v_add_u32_e32 v173, s98, v168
	ds_read_b128 v[214:217], v173
	ds_read_b128 v[218:221], v173 offset:1024
	ds_read_b128 v[222:225], v173 offset:2048
	ds_read_b128 v[226:229], v173 offset:3072
	s_add_u32 s56, s56, 0x160000
	s_addc_u32 s57, s57, 0
	s_mov_b32 m0, s58
	v_lshl_add_u64 v[244:245], s[56:57], 0, v[136:137]
	global_load_lds_dwordx4 v[244:245], off
	v_lshl_add_u64 v[244:245], s[56:57], 0, v[140:141]
	s_mov_b32 m0, s59
	s_nop 0
	global_load_lds_dwordx4 v[244:245], off
	s_waitcnt vmcnt(8) lgkmcnt(0)
	s_barrier
	v_mfma_f32_16x16x32_bf16 v[124:127], v[150:153], v[182:185], v[124:127]
	v_mfma_f32_16x16x32_bf16 v[120:123], v[174:177], v[182:185], v[120:123]
	v_mfma_f32_16x16x32_bf16 v[116:119], v[150:153], v[190:193], v[116:119]
	v_mfma_f32_16x16x32_bf16 v[108:111], v[174:177], v[190:193], v[108:111]
	v_mfma_f32_16x16x32_bf16 v[100:103], v[150:153], v[198:201], v[100:103]
	v_mfma_f32_16x16x32_bf16 v[92:95], v[174:177], v[198:201], v[92:95]
	v_mfma_f32_16x16x32_bf16 v[84:87], v[150:153], v[206:209], v[84:87]
	v_mfma_f32_16x16x32_bf16 v[76:79], v[174:177], v[206:209], v[76:79]
	v_mfma_f32_16x16x32_bf16 v[124:127], v[154:157], v[186:189], v[124:127]
	v_mfma_f32_16x16x32_bf16 v[120:123], v[178:181], v[186:189], v[120:123]
	v_mfma_f32_16x16x32_bf16 v[116:119], v[154:157], v[194:197], v[116:119]
	v_mfma_f32_16x16x32_bf16 v[108:111], v[178:181], v[194:197], v[108:111]
	v_mfma_f32_16x16x32_bf16 v[100:103], v[154:157], v[202:205], v[100:103]
	v_mfma_f32_16x16x32_bf16 v[92:95], v[178:181], v[202:205], v[92:95]
	v_mfma_f32_16x16x32_bf16 v[84:87], v[154:157], v[210:213], v[84:87]
	v_mfma_f32_16x16x32_bf16 v[76:79], v[178:181], v[210:213], v[76:79]
	v_mfma_f32_16x16x32_bf16 v[112:115], v[214:217], v[182:185], v[112:115]
	v_mfma_f32_16x16x32_bf16 v[104:107], v[222:225], v[182:185], v[104:107]
	v_mfma_f32_16x16x32_bf16 v[96:99], v[214:217], v[190:193], v[96:99]
	v_mfma_f32_16x16x32_bf16 v[88:91], v[222:225], v[190:193], v[88:91]
	v_mfma_f32_16x16x32_bf16 v[80:83], v[214:217], v[198:201], v[80:83]
	v_mfma_f32_16x16x32_bf16 v[72:75], v[222:225], v[198:201], v[72:75]
	v_mfma_f32_16x16x32_bf16 v[68:71], v[214:217], v[206:209], v[68:71]
	v_mfma_f32_16x16x32_bf16 v[64:67], v[222:225], v[206:209], v[64:67]
	v_mfma_f32_16x16x32_bf16 v[112:115], v[218:221], v[186:189], v[112:115]
	v_mfma_f32_16x16x32_bf16 v[104:107], v[226:229], v[186:189], v[104:107]
	v_mfma_f32_16x16x32_bf16 v[96:99], v[218:221], v[194:197], v[96:99]
	v_mfma_f32_16x16x32_bf16 v[88:91], v[226:229], v[194:197], v[88:91]
	v_mfma_f32_16x16x32_bf16 v[80:83], v[218:221], v[202:205], v[80:83]
	v_mfma_f32_16x16x32_bf16 v[72:75], v[226:229], v[202:205], v[72:75]
	v_mfma_f32_16x16x32_bf16 v[68:71], v[218:221], v[210:213], v[68:71]
	v_mfma_f32_16x16x32_bf16 v[64:67], v[226:229], v[210:213], v[64:67]
	s_barrier
; #define PG8_STAGE(bufoff, gbase, voff) do { _Pragma("unroll") for (int _i = 0; _i < 2; ++_i) \
;         __builtin_amdgcn_global_load_lds((const unsigned*)((const char*)(gbase) + (voff)[_i]), (LAS unsigned*)(lds + (bufoff) + ldsw + _i * 8192), 16, 0, 0); } while (0)
; #define PG8_LDA(dst, b, h) do { _Pragma("unroll") for (int m = 0; m < 4; ++m) _Pragma("unroll") for (int k = 0; k < 2; ++k) dst[m][k] = *(const LAS bf16x8*)(lds + PG8_SA(b, h) + aoff + m * 2048 + k * 1024); } while (0)
; #define PG8_LDB(dst, b, h) do { _Pragma("unroll") for (int n = 0; n < 2; ++n) _Pragma("unroll") for (int k = 0; k < 2; ++k) dst[n][k] = *(const LAS bf16x8*)(lds + PG8_SB(b, h) + boff + n * 2048 + k * 1024); } while (0)
; #define PG8_MMA(ai, bj, At, Bt) do { __builtin_amdgcn_s_setprio(1); _Pragma("unroll") for (int m = 0; m < 4; ++m) _Pragma("unroll") for (int n = 0; n < 2; ++n) _Pragma("unroll") for (int k = 0; k < 2; ++k) \
;         acc[ai][bj][m][n] = __builtin_amdgcn_mfma_f32_16x16x32_bf16(Bt[n][k], At[m][k], acc[ai][bj][m][n], 0, 0, 0); __builtin_amdgcn_s_setprio(0); } while (0)
; #define PG8_WAIT_V(n) asm volatile("s_waitcnt vmcnt(" #n ")" ::: "memory")
; #define PG8_WAIT_L(n) asm volatile("s_waitcnt lgkmcnt(" #n ")" ::: "memory")
; #define PG8_BAR __builtin_amdgcn_s_barrier()
; #define PG8_SCHED __builtin_amdgcn_sched_barrier(0)
; template <class Epi>
; __device__ __forceinline__ void gemm_phase(LAS unsigned char* lds, const Gemm g, const StaticOrder& S, const Epi& E) {
;     ...
;             PG8_LDB(B1, 1, 1); PG8_STAGE(PG8_SB(1, 0), b3, voffB);
;             PG8_BAR; PG8_WAIT_L(0); PG8_MMA(0, 1, At, B1); PG8_BAR;
;             PG8_LDA(At, 1, 1); PG8_STAGE(PG8_SA(1, 0), a3, voffA);
;             PG8_BAR; PG8_WAIT_L(0); PG8_MMA(1, 0, At, B0); PG8_BAR; PG8_SCHED;
;             PG8_STAGE(PG8_SB(1, 1), b3 + hstepB, voffB);
;             PG8_WAIT_V(6); PG8_BAR; PG8_MMA(1, 1, At, B1); PG8_BAR;
;         }
	ds_read_b128 v[182:185], v171 offset:49152
	ds_read_b128 v[186:189], v171 offset:50176
	ds_read_b128 v[190:193], v171 offset:51200
	ds_read_b128 v[194:197], v171 offset:52224
	ds_read_b128 v[198:201], v171 offset:53248
	ds_read_b128 v[202:205], v171 offset:54272
	ds_read_b128 v[206:209], v171 offset:55296
	ds_read_b128 v[210:213], v171 offset:56320
	s_add_i32 s57, s84, s21
	v_lshl_add_u64 v[158:159], v[158:159], 0, s[22:23]
	s_mov_b32 m0, s57
	global_load_lds_dwordx4 v[158:159], off
	v_lshl_add_u64 v[158:159], v[230:231], 0, s[22:23]
	s_add_i32 m0, s57, 0x2000
	s_nop 0
	global_load_lds_dwordx4 v[158:159], off
	s_mov_b32 m0, s60
	v_lshl_add_u64 v[158:159], v[232:233], 0, s[22:23]
	global_load_lds_dwordx4 v[158:159], off
	v_lshl_add_u64 v[158:159], v[234:235], 0, s[22:23]
	s_mov_b32 m0, s61
	s_nop 0
	global_load_lds_dwordx4 v[158:159], off
	s_add_u32 s54, s54, 0xb0080
	s_addc_u32 s55, s55, 0
	s_add_i32 s56, s98, s21
	v_lshl_add_u64 v[240:241], s[54:55], 0, v[138:139]
	s_mov_b32 m0, s56
	s_nop 0
	global_load_lds_dwordx4 v[240:241], off
	v_lshl_add_u64 v[240:241], s[54:55], 0, v[142:143]
	s_add_i32 m0, s56, 0x2000
	s_nop 0
	global_load_lds_dwordx4 v[240:241], off
	s_waitcnt vmcnt(8) lgkmcnt(0)
	s_barrier
	v_mfma_f32_16x16x32_bf16 v[60:63], v[150:153], v[182:185], v[60:63]
	v_mfma_f32_16x16x32_bf16 v[56:59], v[174:177], v[182:185], v[56:59]
	v_mfma_f32_16x16x32_bf16 v[52:55], v[150:153], v[190:193], v[52:55]
	v_mfma_f32_16x16x32_bf16 v[44:47], v[174:177], v[190:193], v[44:47]
	v_mfma_f32_16x16x32_bf16 v[36:39], v[150:153], v[198:201], v[36:39]
	v_mfma_f32_16x16x32_bf16 v[28:31], v[174:177], v[198:201], v[28:31]
	v_mfma_f32_16x16x32_bf16 v[20:23], v[150:153], v[206:209], v[20:23]
	v_mfma_f32_16x16x32_bf16 v[12:15], v[174:177], v[206:209], v[12:15]
	v_mfma_f32_16x16x32_bf16 v[60:63], v[154:157], v[186:189], v[60:63]
	v_mfma_f32_16x16x32_bf16 v[56:59], v[178:181], v[186:189], v[56:59]
	v_mfma_f32_16x16x32_bf16 v[52:55], v[154:157], v[194:197], v[52:55]
	v_mfma_f32_16x16x32_bf16 v[44:47], v[178:181], v[194:197], v[44:47]
	v_mfma_f32_16x16x32_bf16 v[36:39], v[154:157], v[202:205], v[36:39]
	v_mfma_f32_16x16x32_bf16 v[28:31], v[178:181], v[202:205], v[28:31]
	v_mfma_f32_16x16x32_bf16 v[20:23], v[154:157], v[210:213], v[20:23]
	v_mfma_f32_16x16x32_bf16 v[12:15], v[178:181], v[210:213], v[12:15]
	v_mfma_f32_16x16x32_bf16 v[48:51], v[214:217], v[182:185], v[48:51]
	v_mfma_f32_16x16x32_bf16 v[40:43], v[222:225], v[182:185], v[40:43]
	v_mfma_f32_16x16x32_bf16 v[32:35], v[214:217], v[190:193], v[32:35]
	v_mfma_f32_16x16x32_bf16 v[24:27], v[222:225], v[190:193], v[24:27]
	v_mfma_f32_16x16x32_bf16 v[16:19], v[214:217], v[198:201], v[16:19]
	v_mfma_f32_16x16x32_bf16 v[8:11], v[222:225], v[198:201], v[8:11]
	v_mfma_f32_16x16x32_bf16 v[4:7], v[214:217], v[206:209], v[4:7]
	v_mfma_f32_16x16x32_bf16 v[0:3], v[222:225], v[206:209], v[0:3]
	v_mfma_f32_16x16x32_bf16 v[48:51], v[218:221], v[186:189], v[48:51]
	v_mfma_f32_16x16x32_bf16 v[40:43], v[226:229], v[186:189], v[40:43]
	v_mfma_f32_16x16x32_bf16 v[32:35], v[218:221], v[194:197], v[32:35]
	v_mfma_f32_16x16x32_bf16 v[24:27], v[226:229], v[194:197], v[24:27]
	v_mfma_f32_16x16x32_bf16 v[16:19], v[218:221], v[202:205], v[16:19]
	v_mfma_f32_16x16x32_bf16 v[8:11], v[226:229], v[202:205], v[8:11]
	v_mfma_f32_16x16x32_bf16 v[4:7], v[218:221], v[210:213], v[4:7]
	v_mfma_f32_16x16x32_bf16 v[0:3], v[226:229], v[210:213], v[0:3]
	s_add_u32 s46, s46, 0x100
	s_addc_u32 s47, s47, 0
	s_add_u32 s41, s41, 0x100
	s_addc_u32 s82, s82, 0
	s_cmp_ge_i32 s83, s81
	s_mov_b32 s54, s83
	s_barrier
;     __device__ __forceinline__ void operator()(const f32x4 (&acc)[2][2][4][2], const Unit& u, int wr, int wc, int fr, int fq) const {
;         const int row0 = u.pm * BM + wr * 64 + fr, col0 = u.pn * BM + wc * 32 + 8 * fq;
;         if (u.part) {
;             float* base = tailacc + (size_t)(u.part - 1) * slab - (size_t)tail_row0 * tail_ld;
; #pragma unroll
;             for (int ai = 0; ai < 2; ++ai)
; #pragma unroll
;                 for (int m = 0; m < 4; ++m) { float* rowp = base + (size_t)(row0 + ai * HALF + m * 16) * tail_ld + col0;
; #pragma unroll
;                     for (int bj = 0; bj < 2; ++bj)
; #pragma unroll
;                         for (int n = 0; n < 2; ++n) *(f32x4*)(rowp + bj * HALF + 4 * n) = acc[ai][bj][m][n]; }
;             return;
	s_cbranch_scc0 .LBB0_910
	v_lshl_add_u32 v158, s78, 8, v167
	v_lshl_or_b32 v150, s79, 8, v169
	v_or_b32_e32 v156, 16, v158
	v_or_b32_e32 v154, 32, v158
	v_or_b32_e32 v152, 48, v158
	s_cmp_lg_u32 s80, 0
	v_ashrrev_i32_e32 v151, 31, v150
	v_ashrrev_i32_e32 v159, 31, v158
	v_ashrrev_i32_e32 v157, 31, v156
	v_ashrrev_i32_e32 v155, 31, v154
	v_ashrrev_i32_e32 v153, 31, v152
	s_cbranch_scc0 .LBB0_913
	s_add_i32 s18, s80, -1
	s_lshl_b64 s[46:47], s[18:19], 21
	s_add_u32 s46, s92, s46
	s_addc_u32 s47, s93, s47
	v_lshl_add_u64 v[174:175], v[150:151], 2, s[46:47]
	s_brev_b32 s46, 63
	s_mov_b32 s47, -1
	v_lshl_add_u64 v[174:175], v[174:175], 0, s[46:47]
	v_lshlrev_b64 v[176:177], 12, v[158:159]
	v_lshlrev_b64 v[178:179], 12, v[156:157]
	v_lshl_add_u64 v[176:177], v[174:175], 0, v[176:177]
	v_lshl_add_u64 v[178:179], v[174:175], 0, v[178:179]
	global_store_dwordx4 v[176:177], v[124:127], off
	global_store_dwordx4 v[176:177], v[120:123], off offset:16
	global_store_dwordx4 v[176:177], v[112:115], off offset:512
	global_store_dwordx4 v[176:177], v[104:107], off offset:528
	global_store_dwordx4 v[178:179], v[116:119], off
	global_store_dwordx4 v[178:179], v[108:111], off offset:16
	global_store_dwordx4 v[178:179], v[96:99], off offset:512
	global_store_dwordx4 v[178:179], v[88:91], off offset:528
	v_lshlrev_b64 v[178:179], 12, v[154:155]
	v_lshl_add_u64 v[178:179], v[174:175], 0, v[178:179]
	global_store_dwordx4 v[178:179], v[100:103], off
	global_store_dwordx4 v[178:179], v[92:95], off offset:16
	global_store_dwordx4 v[178:179], v[80:83], off offset:512
	global_store_dwordx4 v[178:179], v[72:75], off offset:528
	v_lshlrev_b64 v[178:179], 12, v[152:153]
	s_mov_b32 s18, 0x80000
	v_lshl_add_u64 v[174:175], v[174:175], 0, v[178:179]
	v_add_co_u32_e32 v178, vcc, s18, v176
	s_mov_b64 s[46:47], 0x80000
	s_nop 0
	v_addc_co_u32_e32 v179, vcc, 0, v177, vcc
	global_store_dwordx4 v[174:175], v[84:87], off
	global_store_dwordx4 v[174:175], v[76:79], off offset:16
	global_store_dwordx4 v[174:175], v[68:71], off offset:512
	global_store_dwordx4 v[174:175], v[64:67], off offset:528
	v_lshl_add_u64 v[174:175], v[176:177], 0, s[46:47]
	global_store_dwordx4 v[178:179], v[60:63], off
	global_store_dwordx4 v[174:175], v[56:59], off offset:16
	global_store_dwordx4 v[174:175], v[48:51], off offset:512
	global_store_dwordx4 v[174:175], v[40:43], off offset:528
	v_add_co_u32_e32 v178, vcc, s67, v176
	s_mov_b64 s[46:47], 0x90000
	s_nop 0
	v_addc_co_u32_e32 v179, vcc, 0, v177, vcc
	v_lshl_add_u64 v[174:175], v[176:177], 0, s[46:47]
	global_store_dwordx4 v[178:179], v[52:55], off
	global_store_dwordx4 v[174:175], v[44:47], off offset:16
	global_store_dwordx4 v[174:175], v[32:35], off offset:512
	global_store_dwordx4 v[174:175], v[24:27], off offset:528
	v_add_co_u32_e32 v178, vcc, s68, v176
	v_lshl_add_u64 v[174:175], v[176:177], 0, s[24:25]
	s_nop 0
	v_addc_co_u32_e32 v179, vcc, 0, v177, vcc
	s_mov_b64 s[46:47], 0xb0000
	global_store_dwordx4 v[178:179], v[36:39], off
	global_store_dwordx4 v[174:175], v[28:31], off offset:16
	global_store_dwordx4 v[174:175], v[16:19], off offset:512
	global_store_dwordx4 v[174:175], v[8:11], off offset:528
	v_lshl_add_u64 v[174:175], v[176:177], 0, s[46:47]
	v_add_co_u32_e32 v176, vcc, 0xb0000, v176
	s_nop 1
	v_addc_co_u32_e32 v177, vcc, 0, v177, vcc
	global_store_dwordx4 v[176:177], v[20:23], off
	global_store_dwordx4 v[174:175], v[12:15], off offset:16
	global_store_dwordx4 v[174:175], v[4:7], off offset:512
	global_store_dwordx4 v[174:175], v[0:3], off offset:528
	s_cbranch_execnz .LBB0_895
	s_branch .LBB0_894

; #define PG8_STAGE(bufoff, gbase, voff) do { _Pragma("unroll") for (int _i = 0; _i < 2; ++_i) \
;         __builtin_amdgcn_global_load_lds((const unsigned*)((const char*)(gbase) + (voff)[_i]), (LAS unsigned*)(lds + (bufoff) + ldsw + _i * 8192), 16, 0, 0); } while (0)
; #define PG8_LDA(dst, b, h) do { _Pragma("unroll") for (int m = 0; m < 4; ++m) _Pragma("unroll") for (int k = 0; k < 2; ++k) dst[m][k] = *(const LAS bf16x8*)(lds + PG8_SA(b, h) + aoff + m * 2048 + k * 1024); } while (0)
; #define PG8_LDB(dst, b, h) do { _Pragma("unroll") for (int n = 0; n < 2; ++n) _Pragma("unroll") for (int k = 0; k < 2; ++k) dst[n][k] = *(const LAS bf16x8*)(lds + PG8_SB(b, h) + boff + n * 2048 + k * 1024); } while (0)
; #define PG8_MMA(ai, bj, At, Bt) do { __builtin_amdgcn_s_setprio(1); _Pragma("unroll") for (int m = 0; m < 4; ++m) _Pragma("unroll") for (int n = 0; n < 2; ++n) _Pragma("unroll") for (int k = 0; k < 2; ++k) \
;         acc[ai][bj][m][n] = __builtin_amdgcn_mfma_f32_16x16x32_bf16(Bt[n][k], At[m][k], acc[ai][bj][m][n], 0, 0, 0); __builtin_amdgcn_s_setprio(0); } while (0)
; #define PG8_WAIT_V(n) asm volatile("s_waitcnt vmcnt(" #n ")" ::: "memory")
; #define PG8_WAIT_L(n) asm volatile("s_waitcnt lgkmcnt(" #n ")" ::: "memory")
; template <class Epi>
; __device__ __forceinline__ void gemm_phase(LAS unsigned char* lds, const Gemm g, const StaticOrder& S, const Epi& E) {
;     ...
;         for (int t = 0; t < nt; t += 2) {
;             const bool last = (t == nt - 2);
;             const char* a1 = cA + (size_t)(t + 1) * kstep;
;             const char* a2 = last ? nA : cA + (size_t)(t + 2) * kstep; const char* b2 = last ? nB : cB + (size_t)(t + 2) * kstep;
;             const char* a3 = a2 + kstep; const char* b3 = b2 + kstep;
;             PG8_LDB(B0, 0, 0); PG8_SCHED; PG8_LDA(At, 0, 0); PG8_STAGE(PG8_SA(1, 1), a1 + hstepA, voffA);
;             PG8_WAIT_L(8); PG8_BAR; PG8_WAIT_L(0); PG8_MMA(0, 0, At, B0); PG8_BAR; PG8_SCHED;
;             PG8_LDB(B1, 0, 1); PG8_STAGE(PG8_SB(0, 0), b2, voffB);
;             PG8_BAR; PG8_WAIT_L(0); PG8_MMA(0, 1, At, B1); PG8_BAR;
;             PG8_LDA(At, 0, 1); PG8_STAGE(PG8_SA(0, 0), a2, voffA);
;             PG8_BAR; PG8_WAIT_L(0); PG8_MMA(1, 0, At, B0); PG8_BAR; PG8_SCHED;
;             PG8_STAGE(PG8_SB(0, 1), b2 + hstepB, voffB);
;             PG8_WAIT_V(6); PG8_BAR; PG8_MMA(1, 1, At, B1); PG8_BAR;
.LBB0_1146:
	s_add_i32 s77, s45, 2
	s_add_u32 s54, s50, 0xfffc0080
	s_addc_u32 s55, s51, -1
	s_cmp_eq_u32 s39, s45
	s_cselect_b32 s57, s49, s55
	s_cselect_b32 s56, s48, s54
	s_cselect_b32 s55, s1, s43
	s_cselect_b32 s54, s0, s41
	ds_read_b128 v[150:153], v129
	ds_read_b128 v[154:157], v129 offset:1024
	ds_read_b128 v[158:161], v129 offset:2048
	ds_read_b128 v[166:169], v129 offset:3072
	ds_read_b128 v[170:173], v163
	ds_read_b128 v[174:177], v163 offset:1024
	ds_read_b128 v[178:181], v163 offset:2048
	ds_read_b128 v[182:185], v163 offset:3072
	ds_read_b128 v[186:189], v163 offset:4096
	ds_read_b128 v[190:193], v163 offset:5120
	ds_read_b128 v[194:197], v163 offset:6144
	ds_read_b128 v[198:201], v163 offset:7168
	ds_read_b128 v[202:205], v164
	ds_read_b128 v[206:209], v164 offset:1024
	ds_read_b128 v[210:213], v164 offset:2048
	ds_read_b128 v[214:217], v164 offset:3072
	v_lshl_add_u64 v[242:243], s[50:51], 0, v[144:145]
	s_add_i32 m0, s33, 0xc000
	global_load_lds_dwordx4 v[242:243], off
	v_lshl_add_u64 v[242:243], s[50:51], 0, v[146:147]
	s_add_i32 m0, s33, 0xe000
	s_nop 0
	global_load_lds_dwordx4 v[242:243], off
	s_waitcnt vmcnt(8) lgkmcnt(0)
	s_barrier
	v_mfma_f32_16x16x32_bf16 v[124:127], v[150:153], v[170:173], v[124:127]
	v_mfma_f32_16x16x32_bf16 v[120:123], v[158:161], v[170:173], v[120:123]
	v_mfma_f32_16x16x32_bf16 v[116:119], v[150:153], v[178:181], v[116:119]
	v_mfma_f32_16x16x32_bf16 v[108:111], v[158:161], v[178:181], v[108:111]
	v_mfma_f32_16x16x32_bf16 v[100:103], v[150:153], v[186:189], v[100:103]
	v_mfma_f32_16x16x32_bf16 v[92:95], v[158:161], v[186:189], v[92:95]
	v_mfma_f32_16x16x32_bf16 v[84:87], v[150:153], v[194:197], v[84:87]
	v_mfma_f32_16x16x32_bf16 v[76:79], v[158:161], v[194:197], v[76:79]
	v_mfma_f32_16x16x32_bf16 v[124:127], v[154:157], v[174:177], v[124:127]
	v_mfma_f32_16x16x32_bf16 v[120:123], v[166:169], v[174:177], v[120:123]
	v_mfma_f32_16x16x32_bf16 v[116:119], v[154:157], v[182:185], v[116:119]
	v_mfma_f32_16x16x32_bf16 v[108:111], v[166:169], v[182:185], v[108:111]
	v_mfma_f32_16x16x32_bf16 v[100:103], v[154:157], v[190:193], v[100:103]
	v_mfma_f32_16x16x32_bf16 v[92:95], v[166:169], v[190:193], v[92:95]
	v_mfma_f32_16x16x32_bf16 v[84:87], v[154:157], v[198:201], v[84:87]
	v_mfma_f32_16x16x32_bf16 v[76:79], v[166:169], v[198:201], v[76:79]
	v_mfma_f32_16x16x32_bf16 v[112:115], v[202:205], v[170:173], v[112:115]
	v_mfma_f32_16x16x32_bf16 v[104:107], v[210:213], v[170:173], v[104:107]
	v_mfma_f32_16x16x32_bf16 v[96:99], v[202:205], v[178:181], v[96:99]
	v_mfma_f32_16x16x32_bf16 v[88:91], v[210:213], v[178:181], v[88:91]
	v_mfma_f32_16x16x32_bf16 v[80:83], v[202:205], v[186:189], v[80:83]
	v_mfma_f32_16x16x32_bf16 v[72:75], v[210:213], v[186:189], v[72:75]
	v_mfma_f32_16x16x32_bf16 v[68:71], v[202:205], v[194:197], v[68:71]
	v_mfma_f32_16x16x32_bf16 v[64:67], v[210:213], v[194:197], v[64:67]
	v_mfma_f32_16x16x32_bf16 v[112:115], v[206:209], v[174:177], v[112:115]
	v_mfma_f32_16x16x32_bf16 v[104:107], v[214:217], v[174:177], v[104:107]
	v_mfma_f32_16x16x32_bf16 v[96:99], v[206:209], v[182:185], v[96:99]
	v_mfma_f32_16x16x32_bf16 v[88:91], v[214:217], v[182:185], v[88:91]
	v_mfma_f32_16x16x32_bf16 v[80:83], v[206:209], v[190:193], v[80:83]
	v_mfma_f32_16x16x32_bf16 v[72:75], v[214:217], v[190:193], v[72:75]
	v_mfma_f32_16x16x32_bf16 v[68:71], v[206:209], v[198:201], v[68:71]
	v_mfma_f32_16x16x32_bf16 v[64:67], v[214:217], v[198:201], v[64:67]
	s_barrier
	ds_read_b128 v[170:173], v163 offset:16384
	ds_read_b128 v[174:177], v163 offset:17408
	ds_read_b128 v[178:181], v163 offset:18432
	ds_read_b128 v[182:185], v163 offset:19456
	ds_read_b128 v[186:189], v163 offset:20480
	ds_read_b128 v[190:193], v163 offset:21504
	ds_read_b128 v[194:197], v163 offset:22528
	ds_read_b128 v[198:201], v163 offset:23552
	s_add_i32 s45, s66, s21
	v_lshl_add_u64 v[218:219], s[54:55], 0, v[138:139]
	s_mov_b32 m0, s45
	global_load_lds_dwordx4 v[218:219], off
	v_lshl_add_u64 v[220:221], s[54:55], 0, v[142:143]
	s_add_i32 m0, s45, 0x2000
	s_nop 0
	global_load_lds_dwordx4 v[220:221], off
	s_mov_b32 m0, s33
	v_lshl_add_u64 v[222:223], s[56:57], 0, v[136:137]
	global_load_lds_dwordx4 v[222:223], off
	v_lshl_add_u64 v[224:225], s[56:57], 0, v[140:141]
	s_mov_b32 m0, s35
	s_nop 0
	global_load_lds_dwordx4 v[224:225], off
	s_add_u32 s78, s54, 0x40000
	s_addc_u32 s79, s55, 0
	s_add_i32 s45, s67, s21
	v_lshl_add_u64 v[240:241], s[78:79], 0, v[138:139]
	s_mov_b32 m0, s45
	s_nop 0
	global_load_lds_dwordx4 v[240:241], off
	v_lshl_add_u64 v[240:241], s[78:79], 0, v[142:143]
	s_add_i32 m0, s45, 0x2000
	s_nop 0
	global_load_lds_dwordx4 v[240:241], off
	s_waitcnt vmcnt(8) lgkmcnt(0)
	s_barrier
; #define PG8_STAGE(bufoff, gbase, voff) do { _Pragma("unroll") for (int _i = 0; _i < 2; ++_i) \
;         __builtin_amdgcn_global_load_lds((const unsigned*)((const char*)(gbase) + (voff)[_i]), (LAS unsigned*)(lds + (bufoff) + ldsw + _i * 8192), 16, 0, 0); } while (0)
; #define PG8_LDA(dst, b, h) do { _Pragma("unroll") for (int m = 0; m < 4; ++m) _Pragma("unroll") for (int k = 0; k < 2; ++k) dst[m][k] = *(const LAS bf16x8*)(lds + PG8_SA(b, h) + aoff + m * 2048 + k * 1024); } while (0)
; #define PG8_LDB(dst, b, h) do { _Pragma("unroll") for (int n = 0; n < 2; ++n) _Pragma("unroll") for (int k = 0; k < 2; ++k) dst[n][k] = *(const LAS bf16x8*)(lds + PG8_SB(b, h) + boff + n * 2048 + k * 1024); } while (0)
; #define PG8_MMA(ai, bj, At, Bt) do { __builtin_amdgcn_s_setprio(1); _Pragma("unroll") for (int m = 0; m < 4; ++m) _Pragma("unroll") for (int n = 0; n < 2; ++n) _Pragma("unroll") for (int k = 0; k < 2; ++k) \
;         acc[ai][bj][m][n] = __builtin_amdgcn_mfma_f32_16x16x32_bf16(Bt[n][k], At[m][k], acc[ai][bj][m][n], 0, 0, 0); __builtin_amdgcn_s_setprio(0); } while (0)
; #define PG8_WAIT_V(n) asm volatile("s_waitcnt vmcnt(" #n ")" ::: "memory")
; #define PG8_WAIT_L(n) asm volatile("s_waitcnt lgkmcnt(" #n ")" ::: "memory")
; #define PG8_BAR __builtin_amdgcn_s_barrier()
; #define PG8_SCHED __builtin_amdgcn_sched_barrier(0)
; template <class Epi>
; __device__ __forceinline__ void gemm_phase(LAS unsigned char* lds, const Gemm g, const StaticOrder& S, const Epi& E) {
;     ...
;             PG8_BAR; PG8_WAIT_L(0); PG8_MMA(1, 0, At, B0); PG8_BAR; PG8_SCHED;
;             PG8_STAGE(PG8_SB(0, 1), b2 + hstepB, voffB);
;             PG8_WAIT_V(6); PG8_BAR; PG8_MMA(1, 1, At, B1); PG8_BAR;
;             PG8_LDB(B0, 1, 0); PG8_SCHED; PG8_LDA(At, 1, 0); PG8_STAGE(PG8_SA(0, 1), a2 + hstepA, voffA);
;             PG8_WAIT_L(8); PG8_BAR; PG8_WAIT_L(0); PG8_MMA(0, 0, At, B0); PG8_BAR; PG8_SCHED;
;             PG8_LDB(B1, 1, 1); PG8_STAGE(PG8_SB(1, 0), b3, voffB);
;             PG8_BAR; PG8_WAIT_L(0); PG8_MMA(0, 1, At, B1); PG8_BAR;
	v_mfma_f32_16x16x32_bf16 v[60:63], v[150:153], v[170:173], v[60:63]
	v_mfma_f32_16x16x32_bf16 v[56:59], v[158:161], v[170:173], v[56:59]
	v_mfma_f32_16x16x32_bf16 v[52:55], v[150:153], v[178:181], v[52:55]
	v_mfma_f32_16x16x32_bf16 v[44:47], v[158:161], v[178:181], v[44:47]
	v_mfma_f32_16x16x32_bf16 v[36:39], v[150:153], v[186:189], v[36:39]
	v_mfma_f32_16x16x32_bf16 v[28:31], v[158:161], v[186:189], v[28:31]
	v_mfma_f32_16x16x32_bf16 v[20:23], v[150:153], v[194:197], v[20:23]
	v_mfma_f32_16x16x32_bf16 v[12:15], v[158:161], v[194:197], v[12:15]
	v_mfma_f32_16x16x32_bf16 v[60:63], v[154:157], v[174:177], v[60:63]
	v_mfma_f32_16x16x32_bf16 v[56:59], v[166:169], v[174:177], v[56:59]
	v_mfma_f32_16x16x32_bf16 v[52:55], v[154:157], v[182:185], v[52:55]
	v_mfma_f32_16x16x32_bf16 v[44:47], v[166:169], v[182:185], v[44:47]
	v_mfma_f32_16x16x32_bf16 v[36:39], v[154:157], v[190:193], v[36:39]
	v_mfma_f32_16x16x32_bf16 v[28:31], v[166:169], v[190:193], v[28:31]
	v_mfma_f32_16x16x32_bf16 v[20:23], v[154:157], v[198:201], v[20:23]
	v_mfma_f32_16x16x32_bf16 v[12:15], v[166:169], v[198:201], v[12:15]
	v_mfma_f32_16x16x32_bf16 v[48:51], v[202:205], v[170:173], v[48:51]
	v_mfma_f32_16x16x32_bf16 v[40:43], v[210:213], v[170:173], v[40:43]
	v_mfma_f32_16x16x32_bf16 v[32:35], v[202:205], v[178:181], v[32:35]
	v_mfma_f32_16x16x32_bf16 v[24:27], v[210:213], v[178:181], v[24:27]
	v_mfma_f32_16x16x32_bf16 v[16:19], v[202:205], v[186:189], v[16:19]
	v_mfma_f32_16x16x32_bf16 v[8:11], v[210:213], v[186:189], v[8:11]
	v_mfma_f32_16x16x32_bf16 v[4:7], v[202:205], v[194:197], v[4:7]
	v_mfma_f32_16x16x32_bf16 v[0:3], v[210:213], v[194:197], v[0:3]
	v_mfma_f32_16x16x32_bf16 v[48:51], v[206:209], v[174:177], v[48:51]
	v_mfma_f32_16x16x32_bf16 v[40:43], v[214:217], v[174:177], v[40:43]
	v_mfma_f32_16x16x32_bf16 v[32:35], v[206:209], v[182:185], v[32:35]
	v_mfma_f32_16x16x32_bf16 v[24:27], v[214:217], v[182:185], v[24:27]
	v_mfma_f32_16x16x32_bf16 v[16:19], v[206:209], v[190:193], v[16:19]
	v_mfma_f32_16x16x32_bf16 v[8:11], v[214:217], v[190:193], v[8:11]
	v_mfma_f32_16x16x32_bf16 v[4:7], v[206:209], v[198:201], v[4:7]
	v_mfma_f32_16x16x32_bf16 v[0:3], v[214:217], v[198:201], v[0:3]
	s_barrier
	s_add_i32 s45, 0, 0x18000
	v_add_u32_e32 v165, s45, v135
	ds_read_b128 v[150:153], v165
	ds_read_b128 v[154:157], v165 offset:1024
	ds_read_b128 v[158:161], v165 offset:2048
	ds_read_b128 v[166:169], v165 offset:3072
	ds_read_b128 v[170:173], v163 offset:32768
	ds_read_b128 v[174:177], v163 offset:33792
	ds_read_b128 v[178:181], v163 offset:34816
	ds_read_b128 v[182:185], v163 offset:35840
	ds_read_b128 v[186:189], v163 offset:36864
	ds_read_b128 v[190:193], v163 offset:37888
	ds_read_b128 v[194:197], v163 offset:38912
	ds_read_b128 v[198:201], v163 offset:39936
	s_add_i32 s98, 0, 0x1c000
	v_add_u32_e32 v165, s98, v135
	ds_read_b128 v[202:205], v165
	ds_read_b128 v[206:209], v165 offset:1024
	ds_read_b128 v[210:213], v165 offset:2048
	ds_read_b128 v[214:217], v165 offset:3072
	s_add_u32 s56, s56, 0x40000
	s_addc_u32 s57, s57, 0
	s_mov_b32 m0, s58
	v_lshl_add_u64 v[244:245], s[56:57], 0, v[136:137]
	global_load_lds_dwordx4 v[244:245], off
	v_lshl_add_u64 v[244:245], s[56:57], 0, v[140:141]
	s_mov_b32 m0, s59
	s_nop 0
	global_load_lds_dwordx4 v[244:245], off
	s_waitcnt vmcnt(8) lgkmcnt(0)
	s_barrier
	v_mfma_f32_16x16x32_bf16 v[124:127], v[150:153], v[170:173], v[124:127]
	v_mfma_f32_16x16x32_bf16 v[120:123], v[158:161], v[170:173], v[120:123]
	v_mfma_f32_16x16x32_bf16 v[116:119], v[150:153], v[178:181], v[116:119]
	v_mfma_f32_16x16x32_bf16 v[108:111], v[158:161], v[178:181], v[108:111]
	v_mfma_f32_16x16x32_bf16 v[100:103], v[150:153], v[186:189], v[100:103]
	v_mfma_f32_16x16x32_bf16 v[92:95], v[158:161], v[186:189], v[92:95]
	v_mfma_f32_16x16x32_bf16 v[84:87], v[150:153], v[194:197], v[84:87]
	v_mfma_f32_16x16x32_bf16 v[76:79], v[158:161], v[194:197], v[76:79]
	v_mfma_f32_16x16x32_bf16 v[124:127], v[154:157], v[174:177], v[124:127]
	v_mfma_f32_16x16x32_bf16 v[120:123], v[166:169], v[174:177], v[120:123]
	v_mfma_f32_16x16x32_bf16 v[116:119], v[154:157], v[182:185], v[116:119]
	v_mfma_f32_16x16x32_bf16 v[108:111], v[166:169], v[182:185], v[108:111]
	v_mfma_f32_16x16x32_bf16 v[100:103], v[154:157], v[190:193], v[100:103]
	v_mfma_f32_16x16x32_bf16 v[92:95], v[166:169], v[190:193], v[92:95]
	v_mfma_f32_16x16x32_bf16 v[84:87], v[154:157], v[198:201], v[84:87]
	v_mfma_f32_16x16x32_bf16 v[76:79], v[166:169], v[198:201], v[76:79]
	v_mfma_f32_16x16x32_bf16 v[112:115], v[202:205], v[170:173], v[112:115]
	v_mfma_f32_16x16x32_bf16 v[104:107], v[210:213], v[170:173], v[104:107]
	v_mfma_f32_16x16x32_bf16 v[96:99], v[202:205], v[178:181], v[96:99]
	v_mfma_f32_16x16x32_bf16 v[88:91], v[210:213], v[178:181], v[88:91]
	v_mfma_f32_16x16x32_bf16 v[80:83], v[202:205], v[186:189], v[80:83]
	v_mfma_f32_16x16x32_bf16 v[72:75], v[210:213], v[186:189], v[72:75]
	v_mfma_f32_16x16x32_bf16 v[68:71], v[202:205], v[194:197], v[68:71]
	v_mfma_f32_16x16x32_bf16 v[64:67], v[210:213], v[194:197], v[64:67]
	v_mfma_f32_16x16x32_bf16 v[112:115], v[206:209], v[174:177], v[112:115]
	v_mfma_f32_16x16x32_bf16 v[104:107], v[214:217], v[174:177], v[104:107]
	v_mfma_f32_16x16x32_bf16 v[96:99], v[206:209], v[182:185], v[96:99]
	v_mfma_f32_16x16x32_bf16 v[88:91], v[214:217], v[182:185], v[88:91]
	v_mfma_f32_16x16x32_bf16 v[80:83], v[206:209], v[190:193], v[80:83]
	v_mfma_f32_16x16x32_bf16 v[72:75], v[214:217], v[190:193], v[72:75]
	v_mfma_f32_16x16x32_bf16 v[68:71], v[206:209], v[198:201], v[68:71]
	v_mfma_f32_16x16x32_bf16 v[64:67], v[214:217], v[198:201], v[64:67]
	s_barrier
; #define PG8_STAGE(bufoff, gbase, voff) do { _Pragma("unroll") for (int _i = 0; _i < 2; ++_i) \
;         __builtin_amdgcn_global_load_lds((const unsigned*)((const char*)(gbase) + (voff)[_i]), (LAS unsigned*)(lds + (bufoff) + ldsw + _i * 8192), 16, 0, 0); } while (0)
; #define PG8_LDA(dst, b, h) do { _Pragma("unroll") for (int m = 0; m < 4; ++m) _Pragma("unroll") for (int k = 0; k < 2; ++k) dst[m][k] = *(const LAS bf16x8*)(lds + PG8_SA(b, h) + aoff + m * 2048 + k * 1024); } while (0)
; #define PG8_LDB(dst, b, h) do { _Pragma("unroll") for (int n = 0; n < 2; ++n) _Pragma("unroll") for (int k = 0; k < 2; ++k) dst[n][k] = *(const LAS bf16x8*)(lds + PG8_SB(b, h) + boff + n * 2048 + k * 1024); } while (0)
; #define PG8_MMA(ai, bj, At, Bt) do { __builtin_amdgcn_s_setprio(1); _Pragma("unroll") for (int m = 0; m < 4; ++m) _Pragma("unroll") for (int n = 0; n < 2; ++n) _Pragma("unroll") for (int k = 0; k < 2; ++k) \
;         acc[ai][bj][m][n] = __builtin_amdgcn_mfma_f32_16x16x32_bf16(Bt[n][k], At[m][k], acc[ai][bj][m][n], 0, 0, 0); __builtin_amdgcn_s_setprio(0); } while (0)
; #define PG8_BAR __builtin_amdgcn_s_barrier()
;     __device__ __forceinline__ void operator()(const f32x4 (&acc)[2][2][4][2], const Unit& u, int wr, int wc, int fr, int fq) const {
;     ...
;         if (u.part) {
;             float* base = tailacc + (size_t)(u.part - 1) * slab - (size_t)tail_row0 * tail_ld;
; #pragma unroll
;             for (int ai = 0; ai < 2; ++ai)
; #pragma unroll
;                 for (int m = 0; m < 4; ++m) { float* rowp = base + (size_t)(row0 + ai * HALF + m * 16) * tail_ld + col0;
; #pragma unroll
;                     for (int bj = 0; bj < 2; ++bj)
; #pragma unroll
;                         for (int n = 0; n < 2; ++n) *(f32x4*)(rowp + bj * HALF + 4 * n) = acc[ai][bj][m][n]; }
;             return;
; template <class Epi>
; __device__ __forceinline__ void gemm_phase(LAS unsigned char* lds, const Gemm g, const StaticOrder& S, const Epi& E) {
;     ...
;             PG8_LDB(B1, 1, 1); PG8_STAGE(PG8_SB(1, 0), b3, voffB);
;             PG8_BAR; PG8_WAIT_L(0); PG8_MMA(0, 1, At, B1); PG8_BAR;
;             PG8_LDA(At, 1, 1); PG8_STAGE(PG8_SA(1, 0), a3, voffA);
;             PG8_BAR; PG8_WAIT_L(0); PG8_MMA(1, 0, At, B0); PG8_BAR; PG8_SCHED;
;             PG8_STAGE(PG8_SB(1, 1), b3 + hstepB, voffB);
;             PG8_WAIT_V(6); PG8_BAR; PG8_MMA(1, 1, At, B1); PG8_BAR;
	ds_read_b128 v[170:173], v163 offset:49152
	ds_read_b128 v[174:177], v163 offset:50176
	ds_read_b128 v[178:181], v163 offset:51200
	ds_read_b128 v[182:185], v163 offset:52224
	ds_read_b128 v[186:189], v163 offset:53248
	ds_read_b128 v[190:193], v163 offset:54272
	ds_read_b128 v[194:197], v163 offset:55296
	ds_read_b128 v[198:201], v163 offset:56320
	s_add_i32 s45, s45, s21
	v_lshl_add_u64 v[218:219], v[218:219], 0, s[12:13]
	s_mov_b32 m0, s45
	global_load_lds_dwordx4 v[218:219], off
	v_lshl_add_u64 v[218:219], v[220:221], 0, s[12:13]
	s_add_i32 m0, s45, 0x2000
	s_nop 0
	global_load_lds_dwordx4 v[218:219], off
	s_mov_b32 m0, s60
	v_lshl_add_u64 v[218:219], v[222:223], 0, s[12:13]
	global_load_lds_dwordx4 v[218:219], off
	v_lshl_add_u64 v[218:219], v[224:225], 0, s[12:13]
	s_mov_b32 m0, s61
	s_nop 0
	global_load_lds_dwordx4 v[218:219], off
	s_add_u32 s54, s54, 0x40080
	s_addc_u32 s55, s55, 0
	s_add_i32 s45, s98, s21
	v_lshl_add_u64 v[240:241], s[54:55], 0, v[138:139]
	s_mov_b32 m0, s45
	s_nop 0
	global_load_lds_dwordx4 v[240:241], off
	v_lshl_add_u64 v[240:241], s[54:55], 0, v[142:143]
	s_add_i32 m0, s45, 0x2000
	s_nop 0
	global_load_lds_dwordx4 v[240:241], off
	s_waitcnt vmcnt(8) lgkmcnt(0)
	s_barrier
	v_mfma_f32_16x16x32_bf16 v[60:63], v[150:153], v[170:173], v[60:63]
	v_mfma_f32_16x16x32_bf16 v[56:59], v[158:161], v[170:173], v[56:59]
	v_mfma_f32_16x16x32_bf16 v[52:55], v[150:153], v[178:181], v[52:55]
	v_mfma_f32_16x16x32_bf16 v[44:47], v[158:161], v[178:181], v[44:47]
	v_mfma_f32_16x16x32_bf16 v[36:39], v[150:153], v[186:189], v[36:39]
	v_mfma_f32_16x16x32_bf16 v[28:31], v[158:161], v[186:189], v[28:31]
	v_mfma_f32_16x16x32_bf16 v[20:23], v[150:153], v[194:197], v[20:23]
	v_mfma_f32_16x16x32_bf16 v[12:15], v[158:161], v[194:197], v[12:15]
	v_mfma_f32_16x16x32_bf16 v[60:63], v[154:157], v[174:177], v[60:63]
	v_mfma_f32_16x16x32_bf16 v[56:59], v[166:169], v[174:177], v[56:59]
	v_mfma_f32_16x16x32_bf16 v[52:55], v[154:157], v[182:185], v[52:55]
	v_mfma_f32_16x16x32_bf16 v[44:47], v[166:169], v[182:185], v[44:47]
	v_mfma_f32_16x16x32_bf16 v[36:39], v[154:157], v[190:193], v[36:39]
	v_mfma_f32_16x16x32_bf16 v[28:31], v[166:169], v[190:193], v[28:31]
	v_mfma_f32_16x16x32_bf16 v[20:23], v[154:157], v[198:201], v[20:23]
	v_mfma_f32_16x16x32_bf16 v[12:15], v[166:169], v[198:201], v[12:15]
	v_mfma_f32_16x16x32_bf16 v[48:51], v[202:205], v[170:173], v[48:51]
	v_mfma_f32_16x16x32_bf16 v[40:43], v[210:213], v[170:173], v[40:43]
	v_mfma_f32_16x16x32_bf16 v[32:35], v[202:205], v[178:181], v[32:35]
	v_mfma_f32_16x16x32_bf16 v[24:27], v[210:213], v[178:181], v[24:27]
	v_mfma_f32_16x16x32_bf16 v[16:19], v[202:205], v[186:189], v[16:19]
	v_mfma_f32_16x16x32_bf16 v[8:11], v[210:213], v[186:189], v[8:11]
	v_mfma_f32_16x16x32_bf16 v[4:7], v[202:205], v[194:197], v[4:7]
	v_mfma_f32_16x16x32_bf16 v[0:3], v[210:213], v[194:197], v[0:3]
	v_mfma_f32_16x16x32_bf16 v[48:51], v[206:209], v[174:177], v[48:51]
	v_mfma_f32_16x16x32_bf16 v[40:43], v[214:217], v[174:177], v[40:43]
	v_mfma_f32_16x16x32_bf16 v[32:35], v[206:209], v[182:185], v[32:35]
	v_mfma_f32_16x16x32_bf16 v[24:27], v[214:217], v[182:185], v[24:27]
	v_mfma_f32_16x16x32_bf16 v[16:19], v[206:209], v[190:193], v[16:19]
	v_mfma_f32_16x16x32_bf16 v[8:11], v[214:217], v[190:193], v[8:11]
	v_mfma_f32_16x16x32_bf16 v[4:7], v[206:209], v[198:201], v[4:7]
	v_mfma_f32_16x16x32_bf16 v[0:3], v[214:217], v[198:201], v[0:3]
	s_add_u32 s50, s50, 0x100
	s_addc_u32 s51, s51, 0
	s_add_u32 s41, s41, 0x100
	s_addc_u32 s43, s43, 0
	s_cmp_ge_i32 s77, s76
	s_mov_b32 s45, s77
	s_barrier
	s_cbranch_scc0 .LBB0_1146
	v_lshl_add_u32 v150, s8, 8, v133
	v_lshl_or_b32 v154, s44, 8, v162
	s_cmp_lg_u32 s75, 0
	v_ashrrev_i32_e32 v155, 31, v154
	v_or_b32_e32 v160, 16, v150
	v_or_b32_e32 v158, 32, v150
	v_or_b32_e32 v156, 48, v150
	s_cbranch_scc0 .LBB0_1149
	s_add_i32 s8, s75, -1
	s_lshl_b64 s[44:45], s[8:9], 21
	s_add_u32 s44, s92, s44
	s_addc_u32 s45, s93, s45
	v_lshl_add_u64 v[152:153], v[154:155], 2, s[44:45]
	v_ashrrev_i32_e32 v151, 31, v150
	v_ashrrev_i32_e32 v161, 31, v160
	v_lshl_add_u64 v[152:153], v[152:153], 0, s[22:23]
	v_lshlrev_b64 v[166:167], 12, v[150:151]
	v_lshlrev_b64 v[168:169], 12, v[160:161]
	v_lshl_add_u64 v[166:167], v[152:153], 0, v[166:167]
	v_lshl_add_u64 v[168:169], v[152:153], 0, v[168:169]
	v_ashrrev_i32_e32 v159, 31, v158
	global_store_dwordx4 v[166:167], v[124:127], off
	global_store_dwordx4 v[166:167], v[120:123], off offset:16
	global_store_dwordx4 v[166:167], v[112:115], off offset:512
	global_store_dwordx4 v[166:167], v[104:107], off offset:528
	global_store_dwordx4 v[168:169], v[116:119], off
	global_store_dwordx4 v[168:169], v[108:111], off offset:16
	global_store_dwordx4 v[168:169], v[96:99], off offset:512
	global_store_dwordx4 v[168:169], v[88:91], off offset:528
	v_lshlrev_b64 v[168:169], 12, v[158:159]
	v_lshl_add_u64 v[168:169], v[152:153], 0, v[168:169]
	v_ashrrev_i32_e32 v157, 31, v156
	global_store_dwordx4 v[168:169], v[100:103], off
	global_store_dwordx4 v[168:169], v[92:95], off offset:16
	global_store_dwordx4 v[168:169], v[80:83], off offset:512
	global_store_dwordx4 v[168:169], v[72:75], off offset:528
	v_lshlrev_b64 v[168:169], 12, v[156:157]
	v_lshl_add_u64 v[152:153], v[152:153], 0, v[168:169]
	v_add_co_u32_e32 v168, vcc, s68, v166
	global_store_dwordx4 v[152:153], v[84:87], off
	global_store_dwordx4 v[152:153], v[76:79], off offset:16
	global_store_dwordx4 v[152:153], v[68:71], off offset:512
	global_store_dwordx4 v[152:153], v[64:67], off offset:528
	v_addc_co_u32_e32 v169, vcc, 0, v167, vcc
	v_lshl_add_u64 v[152:153], v[166:167], 0, s[24:25]
	global_store_dwordx4 v[168:169], v[60:63], off
	global_store_dwordx4 v[152:153], v[56:59], off offset:16
	global_store_dwordx4 v[152:153], v[48:51], off offset:512
	global_store_dwordx4 v[152:153], v[40:43], off offset:528
	v_add_co_u32_e32 v168, vcc, s69, v166
	v_lshl_add_u64 v[152:153], v[166:167], 0, s[26:27]
	s_nop 0
	v_addc_co_u32_e32 v169, vcc, 0, v167, vcc
	global_store_dwordx4 v[168:169], v[52:55], off
	global_store_dwordx4 v[152:153], v[44:47], off offset:16
	global_store_dwordx4 v[152:153], v[32:35], off offset:512
	global_store_dwordx4 v[152:153], v[24:27], off offset:528
	v_add_co_u32_e32 v168, vcc, s70, v166
	v_lshl_add_u64 v[152:153], v[166:167], 0, s[28:29]
	s_nop 0
	v_addc_co_u32_e32 v169, vcc, 0, v167, vcc
	global_store_dwordx4 v[168:169], v[36:39], off
	global_store_dwordx4 v[152:153], v[28:31], off offset:16
	global_store_dwordx4 v[152:153], v[16:19], off offset:512
	global_store_dwordx4 v[152:153], v[8:11], off offset:528
	v_lshl_add_u64 v[152:153], v[166:167], 0, s[36:37]
	v_add_co_u32_e32 v166, vcc, 0xb0000, v166
	s_nop 1
	v_addc_co_u32_e32 v167, vcc, 0, v167, vcc
	global_store_dwordx4 v[166:167], v[20:23], off
	global_store_dwordx4 v[152:153], v[12:15], off offset:16
	global_store_dwordx4 v[152:153], v[4:7], off offset:512
	global_store_dwordx4 v[152:153], v[0:3], off offset:528
	s_cbranch_execnz .LBB0_1131
	s_branch .LBB0_1130
